# duplicate lgkmcnt(0) at each MFMA-segment head removed, on top of prologue+pool+stack version
# baseline (speedup 1.0000x reference)
; #define PG8_STAGE(bufoff, gbase, voff) do { _Pragma("unroll") for (int _i = 0; _i < 2; ++_i) \
;     __builtin_amdgcn_global_load_lds((const unsigned*)((const char*)(gbase) + (voff)[_i]), (LAS unsigned*)(lds + (bufoff) + ldsw + _i * 8192), 16, 0, 0); } while (0)
; #define PG8_LDA(dst, b, h) do { _Pragma("unroll") for (int m = 0; m < 4; ++m) _Pragma("unroll") for (int k = 0; k < 2; ++k) dst[m][k] = *(const LAS bf16x8*)(lds + PG8_SA(b, h) + aoff + m * 2048 + k * 1024); } while (0)
; #define PG8_LDB(dst, b, h) do { _Pragma("unroll") for (int n = 0; n < 2; ++n) _Pragma("unroll") for (int k = 0; k < 2; ++k) dst[n][k] = *(const LAS bf16x8*)(lds + PG8_SB(b, h) + boff + n * 2048 + k * 1024); } while (0)
; #define PG8_MMA(ai, bj, At, Bt) do { __builtin_amdgcn_s_setprio(1); _Pragma("unroll") for (int m = 0; m < 4; ++m) _Pragma("unroll") for (int n = 0; n < 2; ++n) _Pragma("unroll") for (int k = 0; k < 2; ++k) \
;     acc[ai][bj][m][n] = __builtin_amdgcn_mfma_f32_16x16x32_bf16(Bt[n][k], At[m][k], acc[ai][bj][m][n], 0, 0, 0); __builtin_amdgcn_s_setprio(0); } while (0)
; #define PG8_WAIT_V(n) asm volatile("s_waitcnt vmcnt(" #n ")" ::: "memory")
; #define PG8_BAR __builtin_amdgcn_s_barrier()
; template <class Epi>
; DI void gemm_phase(LAS unsigned char* lds, const Gemm g, const Epi& E) {
;     ...
;     const bool has_next = S.next(ui + 1, nxt);
;     const char* nA = has_next ? PG8_APTR(nxt) : cA; const char* nB = has_next ? (const char*)g.Bt + (size_t)nxt.pn * tstepB : cB;
;     for (int t = 0; t < nt; t += 2) {
;       const bool last = (t == nt - 2);
;       const char* a1 = cA + (size_t)(t + 1) * kstep;
;       const char* a2 = last ? nA : cA + (size_t)(t + 2) * kstep; const char* b2 = last ? nB : cB + (size_t)(t + 2) * kstep;
;       const char* a3 = a2 + kstep; const char* b3 = b2 + kstep;
;       PG8_LDB(B0, 0, 0); PG8_SCHED; PG8_LDA(At, 0, 0); PG8_STAGE(PG8_SA(1, 1), a1 + hstepA, voffA);
;       PG8_WAIT_L(8); PG8_BAR; PG8_WAIT_L(0); PG8_MMA(0, 0, At, B0); PG8_BAR; PG8_SCHED;
;       PG8_LDB(B1, 0, 1); PG8_STAGE(PG8_SB(0, 0), b2, voffB);
;       PG8_BAR; PG8_WAIT_L(0); PG8_MMA(0, 1, At, B1); PG8_BAR;
;       PG8_LDA(At, 0, 1); PG8_STAGE(PG8_SA(0, 0), a2, voffA);
;       PG8_BAR; PG8_WAIT_L(0); PG8_MMA(1, 0, At, B0); PG8_BAR; PG8_SCHED;
;       PG8_STAGE(PG8_SB(0, 1), b2 + hstepB, voffB);
;       PG8_WAIT_V(6); PG8_BAR; PG8_MMA(1, 1, At, B1); PG8_BAR;
.LBB0_189:
	s_ashr_i32 s13, s12, 31
	v_cmp_lt_i64_e32 vcc, s[18:19], v[170:171]
	s_lshl_b64 s[18:19], s[12:13], 20
	s_add_u32 s18, s42, s18
	s_addc_u32 s19, s43, s19
	s_and_b64 s[22:23], vcc, exec
	s_cselect_b32 s13, s19, s31
	s_cselect_b32 s55, s18, s30
	s_ashr_i32 s3, s2, 31
	s_lshl_b64 s[22:23], s[2:3], 20
	s_add_u32 s22, s44, s22
	s_addc_u32 s23, s45, s23
	s_and_b64 s[40:41], vcc, exec
	s_cselect_b32 s3, s23, s37
	s_cselect_b32 s56, s22, s36
	s_add_u32 s30, s30, 0x80080
	s_addc_u32 s31, s31, 0
	s_add_u32 s57, s36, 0x100
	s_addc_u32 s58, s37, 0
	s_mov_b32 s59, -2
	v_add_u32_e32 v248, 0x10000, v143
	ds_read_b128 v[146:149], v248
	ds_read_b128 v[150:153], v248 offset:1024
	ds_read_b128 v[154:157], v248 offset:2048
	ds_read_b128 v[158:161], v248 offset:3072
	s_add_i32 m0, s27, 0xc000
	ds_read_b128 v[180:183], v145
	ds_read_b128 v[184:187], v145 offset:1024
	ds_read_b128 v[188:191], v145 offset:2048
	ds_read_b128 v[192:195], v145 offset:3072
	ds_read_b128 v[196:199], v145 offset:4096
	ds_read_b128 v[200:203], v145 offset:5120
	ds_read_b128 v[208:211], v145 offset:6144
	ds_read_b128 v[212:215], v145 offset:7168
	global_load_lds_dwordx4 v138, s[30:31]
	s_add_i32 m0, s27, 0xe000
	s_nop 0
	global_load_lds_dwordx4 v140, s[30:31]
	s_waitcnt lgkmcnt(8)
	s_barrier
	s_setprio 1
	s_waitcnt lgkmcnt(0)
	v_mfma_f32_16x16x32_bf16 v[128:131], v[146:149], v[180:183], 0
	s_add_u32 s36, s30, 0xfff80080
	s_addc_u32 s37, s31, -1
	v_mfma_f32_16x16x32_bf16 v[120:123], v[154:157], v[180:183], 0
	s_add_i32 s60, 0, 0x10000
	v_mfma_f32_16x16x32_bf16 v[112:115], v[146:149], v[188:191], 0
	s_cmp_eq_u32 s59, 28
	s_cselect_b32 s41, s13, s37
	s_cselect_b32 s40, s55, s36
	s_cselect_b32 s37, s3, s58
	s_cselect_b32 s36, s56, s57
	v_mfma_f32_16x16x32_bf16 v[104:107], v[154:157], v[188:191], 0
	v_mfma_f32_16x16x32_bf16 v[96:99], v[146:149], v[196:199], 0
	v_mfma_f32_16x16x32_bf16 v[88:91], v[154:157], v[196:199], 0
	v_mfma_f32_16x16x32_bf16 v[80:83], v[146:149], v[208:211], 0
	v_mfma_f32_16x16x32_bf16 v[72:75], v[154:157], v[208:211], 0
	v_mfma_f32_16x16x32_bf16 v[128:131], v[150:153], v[184:187], v[128:131]
	v_mfma_f32_16x16x32_bf16 v[120:123], v[158:161], v[184:187], v[120:123]
	v_mfma_f32_16x16x32_bf16 v[112:115], v[150:153], v[192:195], v[112:115]
	v_mfma_f32_16x16x32_bf16 v[104:107], v[158:161], v[192:195], v[104:107]
	v_mfma_f32_16x16x32_bf16 v[96:99], v[150:153], v[200:203], v[96:99]
	v_mfma_f32_16x16x32_bf16 v[88:91], v[158:161], v[200:203], v[88:91]
	s_setprio 2
	s_barrier
	v_mfma_f32_16x16x32_bf16 v[80:83], v[150:153], v[212:215], v[80:83]
	v_mfma_f32_16x16x32_bf16 v[72:75], v[158:161], v[212:215], v[72:75]
	s_setprio 0
	s_add_i32 s62, 0, 0x14000
	s_add_i32 s60, s60, s47
	ds_read_b128 v[216:219], v248 offset:16384
	ds_read_b128 v[220:223], v248 offset:17408
	ds_read_b128 v[224:227], v248 offset:18432
	ds_read_b128 v[228:231], v248 offset:19456
	s_add_u32 s98, s36, 0x80
	s_addc_u32 s99, s37, 0
	s_mov_b32 m0, s60
	global_load_lds_dwordx4 v2, s[36:37]
	s_add_i32 m0, s60, 0x2000
	s_nop 0
	global_load_lds_dwordx4 v132, s[36:37]
	s_barrier
	s_setprio 1
	s_waitcnt lgkmcnt(0)
	v_mfma_f32_16x16x32_bf16 v[124:127], v[216:219], v[180:183], 0
	v_mfma_f32_16x16x32_bf16 v[116:119], v[224:227], v[180:183], 0
	v_mfma_f32_16x16x32_bf16 v[108:111], v[216:219], v[188:191], 0
	v_mfma_f32_16x16x32_bf16 v[100:103], v[224:227], v[188:191], 0
	v_mfma_f32_16x16x32_bf16 v[92:95], v[216:219], v[196:199], 0
	v_mfma_f32_16x16x32_bf16 v[84:87], v[224:227], v[196:199], 0
	v_mfma_f32_16x16x32_bf16 v[76:79], v[216:219], v[208:211], 0
	v_mfma_f32_16x16x32_bf16 v[68:71], v[224:227], v[208:211], 0
	v_mfma_f32_16x16x32_bf16 v[124:127], v[220:223], v[184:187], v[124:127]
	v_mfma_f32_16x16x32_bf16 v[116:119], v[228:231], v[184:187], v[116:119]
	v_mfma_f32_16x16x32_bf16 v[108:111], v[220:223], v[192:195], v[108:111]
	v_mfma_f32_16x16x32_bf16 v[100:103], v[228:231], v[192:195], v[100:103]
	v_mfma_f32_16x16x32_bf16 v[92:95], v[220:223], v[200:203], v[92:95]
	v_mfma_f32_16x16x32_bf16 v[84:87], v[228:231], v[200:203], v[84:87]
	s_setprio 2
	s_barrier
	v_mfma_f32_16x16x32_bf16 v[76:79], v[220:223], v[212:215], v[76:79]
	v_mfma_f32_16x16x32_bf16 v[68:71], v[228:231], v[212:215], v[68:71]
	s_setprio 0
	s_mov_b32 m0, s27
	s_add_u32 s100, s40, 0x80
	s_addc_u32 s101, s41, 0
	ds_read_b128 v[180:183], v145 offset:16384
	ds_read_b128 v[184:187], v145 offset:17408
	ds_read_b128 v[188:191], v145 offset:18432
	ds_read_b128 v[192:195], v145 offset:19456
	ds_read_b128 v[196:199], v145 offset:20480
	ds_read_b128 v[200:203], v145 offset:21504
	ds_read_b128 v[208:211], v145 offset:22528
	ds_read_b128 v[212:215], v145 offset:23552
	global_load_lds_dwordx4 v136, s[40:41]
	s_mov_b32 m0, s48
	s_nop 0
	global_load_lds_dwordx4 v134, s[40:41]
	s_waitcnt vmcnt(10)
	s_barrier
	s_setprio 1
	s_waitcnt lgkmcnt(0)
	v_mfma_f32_16x16x32_bf16 v[64:67], v[146:149], v[180:183], 0
	v_mfma_f32_16x16x32_bf16 v[56:59], v[154:157], v[180:183], 0
	v_mfma_f32_16x16x32_bf16 v[48:51], v[146:149], v[188:191], 0
	v_mfma_f32_16x16x32_bf16 v[40:43], v[154:157], v[188:191], 0
	v_mfma_f32_16x16x32_bf16 v[32:35], v[146:149], v[196:199], 0
	v_mfma_f32_16x16x32_bf16 v[24:27], v[154:157], v[196:199], 0
	v_mfma_f32_16x16x32_bf16 v[16:19], v[146:149], v[208:211], 0
	v_mfma_f32_16x16x32_bf16 v[8:11], v[154:157], v[208:211], 0
	v_mfma_f32_16x16x32_bf16 v[64:67], v[150:153], v[184:187], v[64:67]
	v_mfma_f32_16x16x32_bf16 v[56:59], v[158:161], v[184:187], v[56:59]
	v_mfma_f32_16x16x32_bf16 v[48:51], v[150:153], v[192:195], v[48:51]
	v_mfma_f32_16x16x32_bf16 v[40:43], v[158:161], v[192:195], v[40:43]
	v_mfma_f32_16x16x32_bf16 v[32:35], v[150:153], v[200:203], v[32:35]
	v_mfma_f32_16x16x32_bf16 v[24:27], v[158:161], v[200:203], v[24:27]
	s_setprio 2
	s_barrier
; #define PG8_STAGE(bufoff, gbase, voff) do { _Pragma("unroll") for (int _i = 0; _i < 2; ++_i) \
;     __builtin_amdgcn_global_load_lds((const unsigned*)((const char*)(gbase) + (voff)[_i]), (LAS unsigned*)(lds + (bufoff) + ldsw + _i * 8192), 16, 0, 0); } while (0)
; #define PG8_LDA(dst, b, h) do { _Pragma("unroll") for (int m = 0; m < 4; ++m) _Pragma("unroll") for (int k = 0; k < 2; ++k) dst[m][k] = *(const LAS bf16x8*)(lds + PG8_SA(b, h) + aoff + m * 2048 + k * 1024); } while (0)
; #define PG8_LDB(dst, b, h) do { _Pragma("unroll") for (int n = 0; n < 2; ++n) _Pragma("unroll") for (int k = 0; k < 2; ++k) dst[n][k] = *(const LAS bf16x8*)(lds + PG8_SB(b, h) + boff + n * 2048 + k * 1024); } while (0)
; #define PG8_MMA(ai, bj, At, Bt) do { __builtin_amdgcn_s_setprio(1); _Pragma("unroll") for (int m = 0; m < 4; ++m) _Pragma("unroll") for (int n = 0; n < 2; ++n) _Pragma("unroll") for (int k = 0; k < 2; ++k) \
;     acc[ai][bj][m][n] = __builtin_amdgcn_mfma_f32_16x16x32_bf16(Bt[n][k], At[m][k], acc[ai][bj][m][n], 0, 0, 0); __builtin_amdgcn_s_setprio(0); } while (0)
; #define PG8_WAIT_V(n) asm volatile("s_waitcnt vmcnt(" #n ")" ::: "memory")
; #define PG8_WAIT_L(n) asm volatile("s_waitcnt lgkmcnt(" #n ")" ::: "memory")
; #define PG8_BAR __builtin_amdgcn_s_barrier()
; #define PG8_SCHED __builtin_amdgcn_sched_barrier(0)
; template <class Epi>
; DI void gemm_phase(LAS unsigned char* lds, const Gemm g, const Epi& E) {
;     ...
;       PG8_WAIT_V(6); PG8_BAR; PG8_MMA(1, 1, At, B1); PG8_BAR;
;       PG8_LDB(B0, 1, 0); PG8_SCHED; PG8_LDA(At, 1, 0); PG8_STAGE(PG8_SA(0, 1), a2 + hstepA, voffA);
;       PG8_WAIT_L(8); PG8_BAR; PG8_WAIT_L(0); PG8_MMA(0, 0, At, B0); PG8_BAR; PG8_SCHED;
;       PG8_LDB(B1, 1, 1); PG8_STAGE(PG8_SB(1, 0), b3, voffB);
;       PG8_BAR; PG8_WAIT_L(0); PG8_MMA(0, 1, At, B1); PG8_BAR;
;       PG8_LDA(At, 1, 1); PG8_STAGE(PG8_SA(1, 0), a3, voffA);
;       PG8_BAR; PG8_WAIT_L(0); PG8_MMA(1, 0, At, B0); PG8_BAR; PG8_SCHED;
	v_mfma_f32_16x16x32_bf16 v[16:19], v[150:153], v[212:215], v[16:19]
	v_mfma_f32_16x16x32_bf16 v[8:11], v[158:161], v[212:215], v[8:11]
	s_setprio 0
	ds_read_b128 v[146:149], v248 offset:32768
	ds_read_b128 v[150:153], v248 offset:33792
	ds_read_b128 v[154:157], v248 offset:34816
	ds_read_b128 v[158:161], v248 offset:35840
	s_add_u32 s60, s36, 0x80000
	s_addc_u32 s61, s37, 0
	s_add_i32 s62, s62, s47
	s_mov_b32 m0, s62
	s_nop 0
	global_load_lds_dwordx4 v2, s[60:61]
	s_add_i32 m0, s62, 0x2000
	s_nop 0
	global_load_lds_dwordx4 v132, s[60:61]
	s_waitcnt vmcnt(6)
	s_barrier
	s_setprio 1
	v_mfma_f32_16x16x32_bf16 v[60:63], v[216:219], v[180:183], 0
	v_mfma_f32_16x16x32_bf16 v[52:55], v[224:227], v[180:183], 0
	v_mfma_f32_16x16x32_bf16 v[44:47], v[216:219], v[188:191], 0
	v_mfma_f32_16x16x32_bf16 v[36:39], v[224:227], v[188:191], 0
	v_mfma_f32_16x16x32_bf16 v[28:31], v[216:219], v[196:199], 0
	v_mfma_f32_16x16x32_bf16 v[20:23], v[224:227], v[196:199], 0
	v_mfma_f32_16x16x32_bf16 v[12:15], v[216:219], v[208:211], 0
	v_mfma_f32_16x16x32_bf16 v[4:7], v[224:227], v[208:211], 0
	v_mfma_f32_16x16x32_bf16 v[60:63], v[220:223], v[184:187], v[60:63]
	v_mfma_f32_16x16x32_bf16 v[52:55], v[228:231], v[184:187], v[52:55]
	v_mfma_f32_16x16x32_bf16 v[44:47], v[220:223], v[192:195], v[44:47]
	v_mfma_f32_16x16x32_bf16 v[36:39], v[228:231], v[192:195], v[36:39]
	v_mfma_f32_16x16x32_bf16 v[28:31], v[220:223], v[200:203], v[28:31]
	v_mfma_f32_16x16x32_bf16 v[20:23], v[228:231], v[200:203], v[20:23]
	s_setprio 2
	s_barrier
	v_mfma_f32_16x16x32_bf16 v[12:15], v[220:223], v[212:215], v[12:15]
	v_mfma_f32_16x16x32_bf16 v[4:7], v[228:231], v[212:215], v[4:7]
	s_setprio 0
	s_add_i32 s60, 0, 0x18000
	s_add_u32 s40, s40, 0x80000
	s_addc_u32 s41, s41, 0
	s_mov_b32 m0, s49
	ds_read_b128 v[180:183], v145 offset:32768
	ds_read_b128 v[184:187], v145 offset:33792
	ds_read_b128 v[188:191], v145 offset:34816
	ds_read_b128 v[192:195], v145 offset:35840
	ds_read_b128 v[196:199], v145 offset:36864
	ds_read_b128 v[200:203], v145 offset:37888
	ds_read_b128 v[208:211], v145 offset:38912
	ds_read_b128 v[212:215], v145 offset:39936
	global_load_lds_dwordx4 v136, s[40:41]
	s_mov_b32 m0, s50
	s_nop 0
	global_load_lds_dwordx4 v134, s[40:41]
	s_waitcnt lgkmcnt(8)
	s_barrier
	s_setprio 1
	s_waitcnt lgkmcnt(0)
	v_mfma_f32_16x16x32_bf16 v[128:131], v[146:149], v[180:183], v[128:131]
	v_mfma_f32_16x16x32_bf16 v[120:123], v[154:157], v[180:183], v[120:123]
	v_mfma_f32_16x16x32_bf16 v[112:115], v[146:149], v[188:191], v[112:115]
	v_mfma_f32_16x16x32_bf16 v[104:107], v[154:157], v[188:191], v[104:107]
	v_mfma_f32_16x16x32_bf16 v[96:99], v[146:149], v[196:199], v[96:99]
	v_mfma_f32_16x16x32_bf16 v[88:91], v[154:157], v[196:199], v[88:91]
	v_mfma_f32_16x16x32_bf16 v[80:83], v[146:149], v[208:211], v[80:83]
	v_mfma_f32_16x16x32_bf16 v[72:75], v[154:157], v[208:211], v[72:75]
	v_mfma_f32_16x16x32_bf16 v[128:131], v[150:153], v[184:187], v[128:131]
	v_mfma_f32_16x16x32_bf16 v[120:123], v[158:161], v[184:187], v[120:123]
	v_mfma_f32_16x16x32_bf16 v[112:115], v[150:153], v[192:195], v[112:115]
	v_mfma_f32_16x16x32_bf16 v[104:107], v[158:161], v[192:195], v[104:107]
	v_mfma_f32_16x16x32_bf16 v[96:99], v[150:153], v[200:203], v[96:99]
	v_mfma_f32_16x16x32_bf16 v[88:91], v[158:161], v[200:203], v[88:91]
	s_setprio 2
	s_barrier
	v_mfma_f32_16x16x32_bf16 v[80:83], v[150:153], v[212:215], v[80:83]
	v_mfma_f32_16x16x32_bf16 v[72:75], v[158:161], v[212:215], v[72:75]
	s_setprio 0
	s_add_i32 s40, 0, 0x1c000
	s_add_i32 s41, s60, s47
	s_mov_b32 m0, s41
	ds_read_b128 v[216:219], v248 offset:49152
	ds_read_b128 v[220:223], v248 offset:50176
	ds_read_b128 v[224:227], v248 offset:51200
	ds_read_b128 v[228:231], v248 offset:52224
	global_load_lds_dwordx4 v2, s[98:99]
	s_add_i32 m0, s41, 0x2000
	s_nop 0
	global_load_lds_dwordx4 v132, s[98:99]
	s_barrier
	s_setprio 1
	s_waitcnt lgkmcnt(0)
	v_mfma_f32_16x16x32_bf16 v[124:127], v[216:219], v[180:183], v[124:127]
	v_mfma_f32_16x16x32_bf16 v[116:119], v[224:227], v[180:183], v[116:119]
	v_mfma_f32_16x16x32_bf16 v[108:111], v[216:219], v[188:191], v[108:111]
	v_mfma_f32_16x16x32_bf16 v[100:103], v[224:227], v[188:191], v[100:103]
	v_mfma_f32_16x16x32_bf16 v[92:95], v[216:219], v[196:199], v[92:95]
	v_mfma_f32_16x16x32_bf16 v[84:87], v[224:227], v[196:199], v[84:87]
	v_mfma_f32_16x16x32_bf16 v[76:79], v[216:219], v[208:211], v[76:79]
	v_mfma_f32_16x16x32_bf16 v[68:71], v[224:227], v[208:211], v[68:71]
	v_mfma_f32_16x16x32_bf16 v[124:127], v[220:223], v[184:187], v[124:127]
	v_mfma_f32_16x16x32_bf16 v[116:119], v[228:231], v[184:187], v[116:119]
	v_mfma_f32_16x16x32_bf16 v[108:111], v[220:223], v[192:195], v[108:111]
	v_mfma_f32_16x16x32_bf16 v[100:103], v[228:231], v[192:195], v[100:103]
	v_mfma_f32_16x16x32_bf16 v[92:95], v[220:223], v[200:203], v[92:95]
	v_mfma_f32_16x16x32_bf16 v[84:87], v[228:231], v[200:203], v[84:87]
	s_setprio 2
	s_barrier
	v_mfma_f32_16x16x32_bf16 v[76:79], v[220:223], v[212:215], v[76:79]
	v_mfma_f32_16x16x32_bf16 v[68:71], v[228:231], v[212:215], v[68:71]
	s_setprio 0
	s_mov_b32 m0, s51
	ds_read_b128 v[180:183], v145 offset:49152
	ds_read_b128 v[184:187], v145 offset:50176
	ds_read_b128 v[188:191], v145 offset:51200
	ds_read_b128 v[192:195], v145 offset:52224
	ds_read_b128 v[196:199], v145 offset:53248
	ds_read_b128 v[200:203], v145 offset:54272
	ds_read_b128 v[208:211], v145 offset:55296
	ds_read_b128 v[212:215], v145 offset:56320
	global_load_lds_dwordx4 v136, s[100:101]
	s_mov_b32 m0, s52
	s_nop 0
	global_load_lds_dwordx4 v134, s[100:101]
	s_waitcnt vmcnt(10)
	s_barrier
; #define PG8_STAGE(bufoff, gbase, voff) do { _Pragma("unroll") for (int _i = 0; _i < 2; ++_i) \
;     __builtin_amdgcn_global_load_lds((const unsigned*)((const char*)(gbase) + (voff)[_i]), (LAS unsigned*)(lds + (bufoff) + ldsw + _i * 8192), 16, 0, 0); } while (0)
; #define PG8_LDA(dst, b, h) do { _Pragma("unroll") for (int m = 0; m < 4; ++m) _Pragma("unroll") for (int k = 0; k < 2; ++k) dst[m][k] = *(const LAS bf16x8*)(lds + PG8_SA(b, h) + aoff + m * 2048 + k * 1024); } while (0)
; #define PG8_LDB(dst, b, h) do { _Pragma("unroll") for (int n = 0; n < 2; ++n) _Pragma("unroll") for (int k = 0; k < 2; ++k) dst[n][k] = *(const LAS bf16x8*)(lds + PG8_SB(b, h) + boff + n * 2048 + k * 1024); } while (0)
; #define PG8_MMA(ai, bj, At, Bt) do { __builtin_amdgcn_s_setprio(1); _Pragma("unroll") for (int m = 0; m < 4; ++m) _Pragma("unroll") for (int n = 0; n < 2; ++n) _Pragma("unroll") for (int k = 0; k < 2; ++k) \
;     acc[ai][bj][m][n] = __builtin_amdgcn_mfma_f32_16x16x32_bf16(Bt[n][k], At[m][k], acc[ai][bj][m][n], 0, 0, 0); __builtin_amdgcn_s_setprio(0); } while (0)
; #define PG8_WAIT_V(n) asm volatile("s_waitcnt vmcnt(" #n ")" ::: "memory")
; #define PG8_WAIT_L(n) asm volatile("s_waitcnt lgkmcnt(" #n ")" ::: "memory")
; #define PG8_BAR __builtin_amdgcn_s_barrier()
; template <class Epi>
; DI void gemm_phase(LAS unsigned char* lds, const Gemm g, const Epi& E) {
;     ...
;     const bool has_next = S.next(ui + 1, nxt);
;     const char* nA = has_next ? PG8_APTR(nxt) : cA; const char* nB = has_next ? (const char*)g.Bt + (size_t)nxt.pn * tstepB : cB;
;     for (int t = 0; t < nt; t += 2) {
;       const bool last = (t == nt - 2);
;       const char* a1 = cA + (size_t)(t + 1) * kstep;
;       const char* a2 = last ? nA : cA + (size_t)(t + 2) * kstep; const char* b2 = last ? nB : cB + (size_t)(t + 2) * kstep;
;       const char* a3 = a2 + kstep; const char* b3 = b2 + kstep;
;       PG8_LDB(B0, 0, 0); PG8_SCHED; PG8_LDA(At, 0, 0); PG8_STAGE(PG8_SA(1, 1), a1 + hstepA, voffA);
;       PG8_WAIT_L(8); PG8_BAR; PG8_WAIT_L(0); PG8_MMA(0, 0, At, B0); PG8_BAR; PG8_SCHED;
;       PG8_LDB(B1, 0, 1); PG8_STAGE(PG8_SB(0, 0), b2, voffB);
;       PG8_BAR; PG8_WAIT_L(0); PG8_MMA(0, 1, At, B1); PG8_BAR;
;     ...
;       PG8_BAR; PG8_WAIT_L(0); PG8_MMA(1, 0, At, B0); PG8_BAR; PG8_SCHED;
;       PG8_STAGE(PG8_SB(1, 1), b3 + hstepB, voffB);
;       PG8_WAIT_V(6); PG8_BAR; PG8_MMA(1, 1, At, B1); PG8_BAR;
	s_setprio 1
	s_waitcnt lgkmcnt(0)
	v_mfma_f32_16x16x32_bf16 v[64:67], v[146:149], v[180:183], v[64:67]
	v_mfma_f32_16x16x32_bf16 v[56:59], v[154:157], v[180:183], v[56:59]
	v_mfma_f32_16x16x32_bf16 v[48:51], v[146:149], v[188:191], v[48:51]
	v_mfma_f32_16x16x32_bf16 v[40:43], v[154:157], v[188:191], v[40:43]
	v_mfma_f32_16x16x32_bf16 v[32:35], v[146:149], v[196:199], v[32:35]
	v_mfma_f32_16x16x32_bf16 v[24:27], v[154:157], v[196:199], v[24:27]
	v_mfma_f32_16x16x32_bf16 v[16:19], v[146:149], v[208:211], v[16:19]
	v_mfma_f32_16x16x32_bf16 v[8:11], v[154:157], v[208:211], v[8:11]
	v_mfma_f32_16x16x32_bf16 v[64:67], v[150:153], v[184:187], v[64:67]
	v_mfma_f32_16x16x32_bf16 v[56:59], v[158:161], v[184:187], v[56:59]
	v_mfma_f32_16x16x32_bf16 v[48:51], v[150:153], v[192:195], v[48:51]
	v_mfma_f32_16x16x32_bf16 v[40:43], v[158:161], v[192:195], v[40:43]
	v_mfma_f32_16x16x32_bf16 v[32:35], v[150:153], v[200:203], v[32:35]
	v_mfma_f32_16x16x32_bf16 v[24:27], v[158:161], v[200:203], v[24:27]
	s_setprio 2
	s_barrier
	v_mfma_f32_16x16x32_bf16 v[16:19], v[150:153], v[212:215], v[16:19]
	v_mfma_f32_16x16x32_bf16 v[8:11], v[158:161], v[212:215], v[8:11]
	s_setprio 0
	ds_read_b128 v[146:149], v248
	ds_read_b128 v[150:153], v248 offset:1024
	ds_read_b128 v[154:157], v248 offset:2048
	ds_read_b128 v[158:161], v248 offset:3072
	s_add_u32 s36, s36, 0x80080
	s_addc_u32 s37, s37, 0
	s_add_i32 s40, s40, s47
	s_mov_b32 m0, s40
	s_nop 0
	global_load_lds_dwordx4 v2, s[36:37]
	s_add_i32 m0, s40, 0x2000
	s_nop 0
	global_load_lds_dwordx4 v132, s[36:37]
	s_waitcnt vmcnt(6)
	s_barrier
	s_setprio 1
	v_mfma_f32_16x16x32_bf16 v[60:63], v[216:219], v[180:183], v[60:63]
	v_mfma_f32_16x16x32_bf16 v[52:55], v[224:227], v[180:183], v[52:55]
	v_mfma_f32_16x16x32_bf16 v[44:47], v[216:219], v[188:191], v[44:47]
	v_mfma_f32_16x16x32_bf16 v[36:39], v[224:227], v[188:191], v[36:39]
	v_mfma_f32_16x16x32_bf16 v[28:31], v[216:219], v[196:199], v[28:31]
	v_mfma_f32_16x16x32_bf16 v[20:23], v[224:227], v[196:199], v[20:23]
	v_mfma_f32_16x16x32_bf16 v[12:15], v[216:219], v[208:211], v[12:15]
	v_mfma_f32_16x16x32_bf16 v[4:7], v[224:227], v[208:211], v[4:7]
	v_mfma_f32_16x16x32_bf16 v[60:63], v[220:223], v[184:187], v[60:63]
	v_mfma_f32_16x16x32_bf16 v[52:55], v[228:231], v[184:187], v[52:55]
	v_mfma_f32_16x16x32_bf16 v[44:47], v[220:223], v[192:195], v[44:47]
	v_mfma_f32_16x16x32_bf16 v[36:39], v[228:231], v[192:195], v[36:39]
	v_mfma_f32_16x16x32_bf16 v[28:31], v[220:223], v[200:203], v[28:31]
	v_mfma_f32_16x16x32_bf16 v[20:23], v[228:231], v[200:203], v[20:23]
	s_setprio 2
	s_barrier
	v_mfma_f32_16x16x32_bf16 v[12:15], v[220:223], v[212:215], v[12:15]
	v_mfma_f32_16x16x32_bf16 v[4:7], v[228:231], v[212:215], v[4:7]
	s_setprio 0
	s_add_i32 s59, s59, 2
	s_add_u32 s30, s30, 0x100
	s_addc_u32 s31, s31, 0
	s_add_u32 s57, s57, 0x100
	s_addc_u32 s58, s58, 0
	s_cmp_gt_u32 s59, 29
	s_cbranch_scc1 .Lpeel_exit_190
.LBB0_190:
	s_add_i32 m0, s27, 0xc000
	ds_read_b128 v[180:183], v145
	ds_read_b128 v[184:187], v145 offset:1024
	ds_read_b128 v[188:191], v145 offset:2048
	ds_read_b128 v[192:195], v145 offset:3072
	ds_read_b128 v[196:199], v145 offset:4096
	ds_read_b128 v[200:203], v145 offset:5120
	ds_read_b128 v[208:211], v145 offset:6144
	ds_read_b128 v[212:215], v145 offset:7168
	global_load_lds_dwordx4 v138, s[30:31]
	s_add_i32 m0, s27, 0xe000
	s_nop 0
	global_load_lds_dwordx4 v140, s[30:31]
	s_waitcnt lgkmcnt(8)
	s_barrier
	s_setprio 1
	s_waitcnt lgkmcnt(0)
	v_mfma_f32_16x16x32_bf16 v[128:131], v[146:149], v[180:183], v[128:131]
	s_add_u32 s36, s30, 0xfff80080
	s_addc_u32 s37, s31, -1
	v_mfma_f32_16x16x32_bf16 v[120:123], v[154:157], v[180:183], v[120:123]
	s_add_i32 s60, 0, 0x10000
	v_mfma_f32_16x16x32_bf16 v[112:115], v[146:149], v[188:191], v[112:115]
	s_cmp_eq_u32 s59, 28
	s_cselect_b32 s41, s13, s37
	s_cselect_b32 s40, s55, s36
	s_cselect_b32 s37, s3, s58
	s_cselect_b32 s36, s56, s57
	v_mfma_f32_16x16x32_bf16 v[104:107], v[154:157], v[188:191], v[104:107]
	v_mfma_f32_16x16x32_bf16 v[96:99], v[146:149], v[196:199], v[96:99]
	v_mfma_f32_16x16x32_bf16 v[88:91], v[154:157], v[196:199], v[88:91]
	v_mfma_f32_16x16x32_bf16 v[80:83], v[146:149], v[208:211], v[80:83]
	v_mfma_f32_16x16x32_bf16 v[72:75], v[154:157], v[208:211], v[72:75]
	v_mfma_f32_16x16x32_bf16 v[128:131], v[150:153], v[184:187], v[128:131]
	v_mfma_f32_16x16x32_bf16 v[120:123], v[158:161], v[184:187], v[120:123]
	v_mfma_f32_16x16x32_bf16 v[112:115], v[150:153], v[192:195], v[112:115]
	v_mfma_f32_16x16x32_bf16 v[104:107], v[158:161], v[192:195], v[104:107]
	v_mfma_f32_16x16x32_bf16 v[96:99], v[150:153], v[200:203], v[96:99]
	v_mfma_f32_16x16x32_bf16 v[88:91], v[158:161], v[200:203], v[88:91]
	s_setprio 2
	s_barrier
	v_mfma_f32_16x16x32_bf16 v[80:83], v[150:153], v[212:215], v[80:83]
	v_mfma_f32_16x16x32_bf16 v[72:75], v[158:161], v[212:215], v[72:75]
	s_setprio 0
	s_add_i32 s62, 0, 0x14000
	s_add_i32 s60, s60, s47
	ds_read_b128 v[216:219], v248 offset:16384
	ds_read_b128 v[220:223], v248 offset:17408
	ds_read_b128 v[224:227], v248 offset:18432
	ds_read_b128 v[228:231], v248 offset:19456
	s_add_u32 s98, s36, 0x80
	s_addc_u32 s99, s37, 0
	s_mov_b32 m0, s60
	global_load_lds_dwordx4 v2, s[36:37]
	s_add_i32 m0, s60, 0x2000
	s_nop 0
	global_load_lds_dwordx4 v132, s[36:37]
	s_barrier
; #define PG8_STAGE(bufoff, gbase, voff) do { _Pragma("unroll") for (int _i = 0; _i < 2; ++_i) \
;     __builtin_amdgcn_global_load_lds((const unsigned*)((const char*)(gbase) + (voff)[_i]), (LAS unsigned*)(lds + (bufoff) + ldsw + _i * 8192), 16, 0, 0); } while (0)
; #define PG8_LDA(dst, b, h) do { _Pragma("unroll") for (int m = 0; m < 4; ++m) _Pragma("unroll") for (int k = 0; k < 2; ++k) dst[m][k] = *(const LAS bf16x8*)(lds + PG8_SA(b, h) + aoff + m * 2048 + k * 1024); } while (0)
; #define PG8_LDB(dst, b, h) do { _Pragma("unroll") for (int n = 0; n < 2; ++n) _Pragma("unroll") for (int k = 0; k < 2; ++k) dst[n][k] = *(const LAS bf16x8*)(lds + PG8_SB(b, h) + boff + n * 2048 + k * 1024); } while (0)
; #define PG8_MMA(ai, bj, At, Bt) do { __builtin_amdgcn_s_setprio(1); _Pragma("unroll") for (int m = 0; m < 4; ++m) _Pragma("unroll") for (int n = 0; n < 2; ++n) _Pragma("unroll") for (int k = 0; k < 2; ++k) \
;     acc[ai][bj][m][n] = __builtin_amdgcn_mfma_f32_16x16x32_bf16(Bt[n][k], At[m][k], acc[ai][bj][m][n], 0, 0, 0); __builtin_amdgcn_s_setprio(0); } while (0)
; #define PG8_WAIT_V(n) asm volatile("s_waitcnt vmcnt(" #n ")" ::: "memory")
; #define PG8_WAIT_L(n) asm volatile("s_waitcnt lgkmcnt(" #n ")" ::: "memory")
; #define PG8_BAR __builtin_amdgcn_s_barrier()
; #define PG8_SCHED __builtin_amdgcn_sched_barrier(0)
; template <class Epi>
; DI void gemm_phase(LAS unsigned char* lds, const Gemm g, const Epi& E) {
;     ...
;       PG8_BAR; PG8_WAIT_L(0); PG8_MMA(0, 1, At, B1); PG8_BAR;
;       PG8_LDA(At, 0, 1); PG8_STAGE(PG8_SA(0, 0), a2, voffA);
;       PG8_BAR; PG8_WAIT_L(0); PG8_MMA(1, 0, At, B0); PG8_BAR; PG8_SCHED;
;       PG8_STAGE(PG8_SB(0, 1), b2 + hstepB, voffB);
;       PG8_WAIT_V(6); PG8_BAR; PG8_MMA(1, 1, At, B1); PG8_BAR;
;       PG8_LDB(B0, 1, 0); PG8_SCHED; PG8_LDA(At, 1, 0); PG8_STAGE(PG8_SA(0, 1), a2 + hstepA, voffA);
;       PG8_WAIT_L(8); PG8_BAR; PG8_WAIT_L(0); PG8_MMA(0, 0, At, B0); PG8_BAR; PG8_SCHED;
;       PG8_LDB(B1, 1, 1); PG8_STAGE(PG8_SB(1, 0), b3, voffB);
;       PG8_BAR; PG8_WAIT_L(0); PG8_MMA(0, 1, At, B1); PG8_BAR;
	s_setprio 1
	s_waitcnt lgkmcnt(0)
	v_mfma_f32_16x16x32_bf16 v[124:127], v[216:219], v[180:183], v[124:127]
	v_mfma_f32_16x16x32_bf16 v[116:119], v[224:227], v[180:183], v[116:119]
	v_mfma_f32_16x16x32_bf16 v[108:111], v[216:219], v[188:191], v[108:111]
	v_mfma_f32_16x16x32_bf16 v[100:103], v[224:227], v[188:191], v[100:103]
	v_mfma_f32_16x16x32_bf16 v[92:95], v[216:219], v[196:199], v[92:95]
	v_mfma_f32_16x16x32_bf16 v[84:87], v[224:227], v[196:199], v[84:87]
	v_mfma_f32_16x16x32_bf16 v[76:79], v[216:219], v[208:211], v[76:79]
	v_mfma_f32_16x16x32_bf16 v[68:71], v[224:227], v[208:211], v[68:71]
	v_mfma_f32_16x16x32_bf16 v[124:127], v[220:223], v[184:187], v[124:127]
	v_mfma_f32_16x16x32_bf16 v[116:119], v[228:231], v[184:187], v[116:119]
	v_mfma_f32_16x16x32_bf16 v[108:111], v[220:223], v[192:195], v[108:111]
	v_mfma_f32_16x16x32_bf16 v[100:103], v[228:231], v[192:195], v[100:103]
	v_mfma_f32_16x16x32_bf16 v[92:95], v[220:223], v[200:203], v[92:95]
	v_mfma_f32_16x16x32_bf16 v[84:87], v[228:231], v[200:203], v[84:87]
	s_setprio 2
	s_barrier
	v_mfma_f32_16x16x32_bf16 v[76:79], v[220:223], v[212:215], v[76:79]
	v_mfma_f32_16x16x32_bf16 v[68:71], v[228:231], v[212:215], v[68:71]
	s_setprio 0
	s_mov_b32 m0, s27
	s_add_u32 s100, s40, 0x80
	s_addc_u32 s101, s41, 0
	ds_read_b128 v[180:183], v145 offset:16384
	ds_read_b128 v[184:187], v145 offset:17408
	ds_read_b128 v[188:191], v145 offset:18432
	ds_read_b128 v[192:195], v145 offset:19456
	ds_read_b128 v[196:199], v145 offset:20480
	ds_read_b128 v[200:203], v145 offset:21504
	ds_read_b128 v[208:211], v145 offset:22528
	ds_read_b128 v[212:215], v145 offset:23552
	global_load_lds_dwordx4 v136, s[40:41]
	s_mov_b32 m0, s48
	s_nop 0
	global_load_lds_dwordx4 v134, s[40:41]
	s_waitcnt vmcnt(10)
	s_barrier
	s_setprio 1
	s_waitcnt lgkmcnt(0)
	v_mfma_f32_16x16x32_bf16 v[64:67], v[146:149], v[180:183], v[64:67]
	v_mfma_f32_16x16x32_bf16 v[56:59], v[154:157], v[180:183], v[56:59]
	v_mfma_f32_16x16x32_bf16 v[48:51], v[146:149], v[188:191], v[48:51]
	v_mfma_f32_16x16x32_bf16 v[40:43], v[154:157], v[188:191], v[40:43]
	v_mfma_f32_16x16x32_bf16 v[32:35], v[146:149], v[196:199], v[32:35]
	v_mfma_f32_16x16x32_bf16 v[24:27], v[154:157], v[196:199], v[24:27]
	v_mfma_f32_16x16x32_bf16 v[16:19], v[146:149], v[208:211], v[16:19]
	v_mfma_f32_16x16x32_bf16 v[8:11], v[154:157], v[208:211], v[8:11]
	v_mfma_f32_16x16x32_bf16 v[64:67], v[150:153], v[184:187], v[64:67]
	v_mfma_f32_16x16x32_bf16 v[56:59], v[158:161], v[184:187], v[56:59]
	v_mfma_f32_16x16x32_bf16 v[48:51], v[150:153], v[192:195], v[48:51]
	v_mfma_f32_16x16x32_bf16 v[40:43], v[158:161], v[192:195], v[40:43]
	v_mfma_f32_16x16x32_bf16 v[32:35], v[150:153], v[200:203], v[32:35]
	v_mfma_f32_16x16x32_bf16 v[24:27], v[158:161], v[200:203], v[24:27]
	s_setprio 2
	s_barrier
	v_mfma_f32_16x16x32_bf16 v[16:19], v[150:153], v[212:215], v[16:19]
	v_mfma_f32_16x16x32_bf16 v[8:11], v[158:161], v[212:215], v[8:11]
	s_setprio 0
	ds_read_b128 v[146:149], v248 offset:32768
	ds_read_b128 v[150:153], v248 offset:33792
	ds_read_b128 v[154:157], v248 offset:34816
	ds_read_b128 v[158:161], v248 offset:35840
	s_add_u32 s60, s36, 0x80000
	s_addc_u32 s61, s37, 0
	s_add_i32 s62, s62, s47
	s_mov_b32 m0, s62
	s_nop 0
	global_load_lds_dwordx4 v2, s[60:61]
	s_add_i32 m0, s62, 0x2000
	s_nop 0
	global_load_lds_dwordx4 v132, s[60:61]
	s_waitcnt vmcnt(6)
	s_barrier
	s_setprio 1
	v_mfma_f32_16x16x32_bf16 v[60:63], v[216:219], v[180:183], v[60:63]
	v_mfma_f32_16x16x32_bf16 v[52:55], v[224:227], v[180:183], v[52:55]
	v_mfma_f32_16x16x32_bf16 v[44:47], v[216:219], v[188:191], v[44:47]
	v_mfma_f32_16x16x32_bf16 v[36:39], v[224:227], v[188:191], v[36:39]
	v_mfma_f32_16x16x32_bf16 v[28:31], v[216:219], v[196:199], v[28:31]
	v_mfma_f32_16x16x32_bf16 v[20:23], v[224:227], v[196:199], v[20:23]
	v_mfma_f32_16x16x32_bf16 v[12:15], v[216:219], v[208:211], v[12:15]
	v_mfma_f32_16x16x32_bf16 v[4:7], v[224:227], v[208:211], v[4:7]
	v_mfma_f32_16x16x32_bf16 v[60:63], v[220:223], v[184:187], v[60:63]
	v_mfma_f32_16x16x32_bf16 v[52:55], v[228:231], v[184:187], v[52:55]
	v_mfma_f32_16x16x32_bf16 v[44:47], v[220:223], v[192:195], v[44:47]
	v_mfma_f32_16x16x32_bf16 v[36:39], v[228:231], v[192:195], v[36:39]
	v_mfma_f32_16x16x32_bf16 v[28:31], v[220:223], v[200:203], v[28:31]
	v_mfma_f32_16x16x32_bf16 v[20:23], v[228:231], v[200:203], v[20:23]
	s_setprio 2
	s_barrier
	v_mfma_f32_16x16x32_bf16 v[12:15], v[220:223], v[212:215], v[12:15]
	v_mfma_f32_16x16x32_bf16 v[4:7], v[228:231], v[212:215], v[4:7]
	s_setprio 0
	s_add_i32 s60, 0, 0x18000
	s_add_u32 s40, s40, 0x80000
	s_addc_u32 s41, s41, 0
	s_mov_b32 m0, s49
	ds_read_b128 v[180:183], v145 offset:32768
	ds_read_b128 v[184:187], v145 offset:33792
	ds_read_b128 v[188:191], v145 offset:34816
	ds_read_b128 v[192:195], v145 offset:35840
	ds_read_b128 v[196:199], v145 offset:36864
	ds_read_b128 v[200:203], v145 offset:37888
	ds_read_b128 v[208:211], v145 offset:38912
	ds_read_b128 v[212:215], v145 offset:39936
	global_load_lds_dwordx4 v136, s[40:41]
	s_mov_b32 m0, s50
	s_nop 0
	global_load_lds_dwordx4 v134, s[40:41]
	s_waitcnt lgkmcnt(8)
	s_barrier
	s_setprio 1
	s_waitcnt lgkmcnt(0)
	v_mfma_f32_16x16x32_bf16 v[128:131], v[146:149], v[180:183], v[128:131]
	v_mfma_f32_16x16x32_bf16 v[120:123], v[154:157], v[180:183], v[120:123]
	v_mfma_f32_16x16x32_bf16 v[112:115], v[146:149], v[188:191], v[112:115]
	v_mfma_f32_16x16x32_bf16 v[104:107], v[154:157], v[188:191], v[104:107]
	v_mfma_f32_16x16x32_bf16 v[96:99], v[146:149], v[196:199], v[96:99]
	v_mfma_f32_16x16x32_bf16 v[88:91], v[154:157], v[196:199], v[88:91]
	v_mfma_f32_16x16x32_bf16 v[80:83], v[146:149], v[208:211], v[80:83]
	v_mfma_f32_16x16x32_bf16 v[72:75], v[154:157], v[208:211], v[72:75]
	v_mfma_f32_16x16x32_bf16 v[128:131], v[150:153], v[184:187], v[128:131]
	v_mfma_f32_16x16x32_bf16 v[120:123], v[158:161], v[184:187], v[120:123]
	v_mfma_f32_16x16x32_bf16 v[112:115], v[150:153], v[192:195], v[112:115]
	v_mfma_f32_16x16x32_bf16 v[104:107], v[158:161], v[192:195], v[104:107]
	v_mfma_f32_16x16x32_bf16 v[96:99], v[150:153], v[200:203], v[96:99]
	v_mfma_f32_16x16x32_bf16 v[88:91], v[158:161], v[200:203], v[88:91]
	s_setprio 2
	s_barrier
; #define PG8_STAGE(bufoff, gbase, voff) do { _Pragma("unroll") for (int _i = 0; _i < 2; ++_i) \
;     __builtin_amdgcn_global_load_lds((const unsigned*)((const char*)(gbase) + (voff)[_i]), (LAS unsigned*)(lds + (bufoff) + ldsw + _i * 8192), 16, 0, 0); } while (0)
; #define PG8_LDA(dst, b, h) do { _Pragma("unroll") for (int m = 0; m < 4; ++m) _Pragma("unroll") for (int k = 0; k < 2; ++k) dst[m][k] = *(const LAS bf16x8*)(lds + PG8_SA(b, h) + aoff + m * 2048 + k * 1024); } while (0)
; #define PG8_MMA(ai, bj, At, Bt) do { __builtin_amdgcn_s_setprio(1); _Pragma("unroll") for (int m = 0; m < 4; ++m) _Pragma("unroll") for (int n = 0; n < 2; ++n) _Pragma("unroll") for (int k = 0; k < 2; ++k) \
;     acc[ai][bj][m][n] = __builtin_amdgcn_mfma_f32_16x16x32_bf16(Bt[n][k], At[m][k], acc[ai][bj][m][n], 0, 0, 0); __builtin_amdgcn_s_setprio(0); } while (0)
; #define PG8_WAIT_V(n) asm volatile("s_waitcnt vmcnt(" #n ")" ::: "memory")
; #define PG8_WAIT_L(n) asm volatile("s_waitcnt lgkmcnt(" #n ")" ::: "memory")
; #define PG8_BAR __builtin_amdgcn_s_barrier()
; #define PG8_SCHED __builtin_amdgcn_sched_barrier(0)
; template <class Epi>
; DI void gemm_phase(LAS unsigned char* lds, const Gemm g, const Epi& E) {
;     ...
;       PG8_BAR; PG8_WAIT_L(0); PG8_MMA(0, 1, At, B1); PG8_BAR;
;       PG8_LDA(At, 1, 1); PG8_STAGE(PG8_SA(1, 0), a3, voffA);
;       PG8_BAR; PG8_WAIT_L(0); PG8_MMA(1, 0, At, B0); PG8_BAR; PG8_SCHED;
;       PG8_STAGE(PG8_SB(1, 1), b3 + hstepB, voffB);
;       PG8_WAIT_V(6); PG8_BAR; PG8_MMA(1, 1, At, B1); PG8_BAR;
	v_mfma_f32_16x16x32_bf16 v[80:83], v[150:153], v[212:215], v[80:83]
	v_mfma_f32_16x16x32_bf16 v[72:75], v[158:161], v[212:215], v[72:75]
	s_setprio 0
	s_add_i32 s40, 0, 0x1c000
	s_add_i32 s41, s60, s47
	s_mov_b32 m0, s41
	ds_read_b128 v[216:219], v248 offset:49152
	ds_read_b128 v[220:223], v248 offset:50176
	ds_read_b128 v[224:227], v248 offset:51200
	ds_read_b128 v[228:231], v248 offset:52224
	global_load_lds_dwordx4 v2, s[98:99]
	s_add_i32 m0, s41, 0x2000
	s_nop 0
	global_load_lds_dwordx4 v132, s[98:99]
	s_barrier
	s_setprio 1
	s_waitcnt lgkmcnt(0)
	v_mfma_f32_16x16x32_bf16 v[124:127], v[216:219], v[180:183], v[124:127]
	v_mfma_f32_16x16x32_bf16 v[116:119], v[224:227], v[180:183], v[116:119]
	v_mfma_f32_16x16x32_bf16 v[108:111], v[216:219], v[188:191], v[108:111]
	v_mfma_f32_16x16x32_bf16 v[100:103], v[224:227], v[188:191], v[100:103]
	v_mfma_f32_16x16x32_bf16 v[92:95], v[216:219], v[196:199], v[92:95]
	v_mfma_f32_16x16x32_bf16 v[84:87], v[224:227], v[196:199], v[84:87]
	v_mfma_f32_16x16x32_bf16 v[76:79], v[216:219], v[208:211], v[76:79]
	v_mfma_f32_16x16x32_bf16 v[68:71], v[224:227], v[208:211], v[68:71]
	v_mfma_f32_16x16x32_bf16 v[124:127], v[220:223], v[184:187], v[124:127]
	v_mfma_f32_16x16x32_bf16 v[116:119], v[228:231], v[184:187], v[116:119]
	v_mfma_f32_16x16x32_bf16 v[108:111], v[220:223], v[192:195], v[108:111]
	v_mfma_f32_16x16x32_bf16 v[100:103], v[228:231], v[192:195], v[100:103]
	v_mfma_f32_16x16x32_bf16 v[92:95], v[220:223], v[200:203], v[92:95]
	v_mfma_f32_16x16x32_bf16 v[84:87], v[228:231], v[200:203], v[84:87]
	s_setprio 2
	s_barrier
	v_mfma_f32_16x16x32_bf16 v[76:79], v[220:223], v[212:215], v[76:79]
	v_mfma_f32_16x16x32_bf16 v[68:71], v[228:231], v[212:215], v[68:71]
	s_setprio 0
	s_mov_b32 m0, s51
	ds_read_b128 v[180:183], v145 offset:49152
	ds_read_b128 v[184:187], v145 offset:50176
	ds_read_b128 v[188:191], v145 offset:51200
	ds_read_b128 v[192:195], v145 offset:52224
	ds_read_b128 v[196:199], v145 offset:53248
	ds_read_b128 v[200:203], v145 offset:54272
	ds_read_b128 v[208:211], v145 offset:55296
	ds_read_b128 v[212:215], v145 offset:56320
	global_load_lds_dwordx4 v136, s[100:101]
	s_mov_b32 m0, s52
	s_nop 0
	global_load_lds_dwordx4 v134, s[100:101]
	s_waitcnt vmcnt(10)
	s_barrier
	s_setprio 1
	s_waitcnt lgkmcnt(0)
	v_mfma_f32_16x16x32_bf16 v[64:67], v[146:149], v[180:183], v[64:67]
	v_mfma_f32_16x16x32_bf16 v[56:59], v[154:157], v[180:183], v[56:59]
	v_mfma_f32_16x16x32_bf16 v[48:51], v[146:149], v[188:191], v[48:51]
	v_mfma_f32_16x16x32_bf16 v[40:43], v[154:157], v[188:191], v[40:43]
	v_mfma_f32_16x16x32_bf16 v[32:35], v[146:149], v[196:199], v[32:35]
	v_mfma_f32_16x16x32_bf16 v[24:27], v[154:157], v[196:199], v[24:27]
	v_mfma_f32_16x16x32_bf16 v[16:19], v[146:149], v[208:211], v[16:19]
	v_mfma_f32_16x16x32_bf16 v[8:11], v[154:157], v[208:211], v[8:11]
	v_mfma_f32_16x16x32_bf16 v[64:67], v[150:153], v[184:187], v[64:67]
	v_mfma_f32_16x16x32_bf16 v[56:59], v[158:161], v[184:187], v[56:59]
	v_mfma_f32_16x16x32_bf16 v[48:51], v[150:153], v[192:195], v[48:51]
	v_mfma_f32_16x16x32_bf16 v[40:43], v[158:161], v[192:195], v[40:43]
	v_mfma_f32_16x16x32_bf16 v[32:35], v[150:153], v[200:203], v[32:35]
	v_mfma_f32_16x16x32_bf16 v[24:27], v[158:161], v[200:203], v[24:27]
	s_setprio 2
	s_barrier
	v_mfma_f32_16x16x32_bf16 v[16:19], v[150:153], v[212:215], v[16:19]
	v_mfma_f32_16x16x32_bf16 v[8:11], v[158:161], v[212:215], v[8:11]
	s_setprio 0
	ds_read_b128 v[146:149], v248
	ds_read_b128 v[150:153], v248 offset:1024
	ds_read_b128 v[154:157], v248 offset:2048
	ds_read_b128 v[158:161], v248 offset:3072
	s_add_u32 s36, s36, 0x80080
	s_addc_u32 s37, s37, 0
	s_add_i32 s40, s40, s47
	s_mov_b32 m0, s40
	s_nop 0
	global_load_lds_dwordx4 v2, s[36:37]
	s_add_i32 m0, s40, 0x2000
	s_nop 0
	global_load_lds_dwordx4 v132, s[36:37]
	s_waitcnt vmcnt(6)
	s_barrier
	s_setprio 1
	v_mfma_f32_16x16x32_bf16 v[60:63], v[216:219], v[180:183], v[60:63]
	v_mfma_f32_16x16x32_bf16 v[52:55], v[224:227], v[180:183], v[52:55]
	v_mfma_f32_16x16x32_bf16 v[44:47], v[216:219], v[188:191], v[44:47]
	v_mfma_f32_16x16x32_bf16 v[36:39], v[224:227], v[188:191], v[36:39]
	v_mfma_f32_16x16x32_bf16 v[28:31], v[216:219], v[196:199], v[28:31]
	v_mfma_f32_16x16x32_bf16 v[20:23], v[224:227], v[196:199], v[20:23]
	v_mfma_f32_16x16x32_bf16 v[12:15], v[216:219], v[208:211], v[12:15]
	v_mfma_f32_16x16x32_bf16 v[4:7], v[224:227], v[208:211], v[4:7]
	v_mfma_f32_16x16x32_bf16 v[60:63], v[220:223], v[184:187], v[60:63]
	v_mfma_f32_16x16x32_bf16 v[52:55], v[228:231], v[184:187], v[52:55]
	v_mfma_f32_16x16x32_bf16 v[44:47], v[220:223], v[192:195], v[44:47]
	v_mfma_f32_16x16x32_bf16 v[36:39], v[228:231], v[192:195], v[36:39]
	v_mfma_f32_16x16x32_bf16 v[28:31], v[220:223], v[200:203], v[28:31]
	v_mfma_f32_16x16x32_bf16 v[20:23], v[228:231], v[200:203], v[20:23]
	s_setprio 2
	s_barrier
	v_mfma_f32_16x16x32_bf16 v[12:15], v[220:223], v[212:215], v[12:15]
	v_mfma_f32_16x16x32_bf16 v[4:7], v[228:231], v[212:215], v[4:7]
	s_setprio 0
	s_add_i32 s59, s59, 2
	s_add_u32 s30, s30, 0x100
	s_addc_u32 s31, s31, 0
	s_add_u32 s57, s57, 0x100
	s_addc_u32 s58, s58, 0
	s_cmp_gt_u32 s59, 29
	s_cbranch_scc0 .LBB0_190

; #define PG8_STAGE(bufoff, gbase, voff) do { _Pragma("unroll") for (int _i = 0; _i < 2; ++_i) \
;     __builtin_amdgcn_global_load_lds((const unsigned*)((const char*)(gbase) + (voff)[_i]), (LAS unsigned*)(lds + (bufoff) + ldsw + _i * 8192), 16, 0, 0); } while (0)
; #define PG8_LDA(dst, b, h) do { _Pragma("unroll") for (int m = 0; m < 4; ++m) _Pragma("unroll") for (int k = 0; k < 2; ++k) dst[m][k] = *(const LAS bf16x8*)(lds + PG8_SA(b, h) + aoff + m * 2048 + k * 1024); } while (0)
; #define PG8_LDB(dst, b, h) do { _Pragma("unroll") for (int n = 0; n < 2; ++n) _Pragma("unroll") for (int k = 0; k < 2; ++k) dst[n][k] = *(const LAS bf16x8*)(lds + PG8_SB(b, h) + boff + n * 2048 + k * 1024); } while (0)
; #define PG8_MMA(ai, bj, At, Bt) do { __builtin_amdgcn_s_setprio(1); _Pragma("unroll") for (int m = 0; m < 4; ++m) _Pragma("unroll") for (int n = 0; n < 2; ++n) _Pragma("unroll") for (int k = 0; k < 2; ++k) \
;     acc[ai][bj][m][n] = __builtin_amdgcn_mfma_f32_16x16x32_bf16(Bt[n][k], At[m][k], acc[ai][bj][m][n], 0, 0, 0); __builtin_amdgcn_s_setprio(0); } while (0)
; #define PG8_WAIT_V(n) asm volatile("s_waitcnt vmcnt(" #n ")" ::: "memory")
; #define PG8_BAR __builtin_amdgcn_s_barrier()
; template <class Epi>
; DI void gemm_phase(LAS unsigned char* lds, const Gemm g, const Epi& E) {
;     ...
;     const bool has_next = S.next(ui + 1, nxt);
;     const char* nA = has_next ? PG8_APTR(nxt) : cA; const char* nB = has_next ? (const char*)g.Bt + (size_t)nxt.pn * tstepB : cB;
;     for (int t = 0; t < nt; t += 2) {
;       const bool last = (t == nt - 2);
;       const char* a1 = cA + (size_t)(t + 1) * kstep;
;       const char* a2 = last ? nA : cA + (size_t)(t + 2) * kstep; const char* b2 = last ? nB : cB + (size_t)(t + 2) * kstep;
;       const char* a3 = a2 + kstep; const char* b3 = b2 + kstep;
;       PG8_LDB(B0, 0, 0); PG8_SCHED; PG8_LDA(At, 0, 0); PG8_STAGE(PG8_SA(1, 1), a1 + hstepA, voffA);
;       PG8_WAIT_L(8); PG8_BAR; PG8_WAIT_L(0); PG8_MMA(0, 0, At, B0); PG8_BAR; PG8_SCHED;
;       PG8_LDB(B1, 0, 1); PG8_STAGE(PG8_SB(0, 0), b2, voffB);
;       PG8_BAR; PG8_WAIT_L(0); PG8_MMA(0, 1, At, B1); PG8_BAR;
;       PG8_LDA(At, 0, 1); PG8_STAGE(PG8_SA(0, 0), a2, voffA);
;       PG8_BAR; PG8_WAIT_L(0); PG8_MMA(1, 0, At, B0); PG8_BAR; PG8_SCHED;
;       PG8_STAGE(PG8_SB(0, 1), b2 + hstepB, voffB);
;       PG8_WAIT_V(6); PG8_BAR; PG8_MMA(1, 1, At, B1); PG8_BAR;
.LBB0_224:
	s_ashr_i32 s27, s26, 31
	v_cmp_lt_i64_e32 vcc, s[30:31], v[174:175]
	s_lshl_b64 s[30:31], s[26:27], 20
	s_add_u32 s30, s49, s30
	s_addc_u32 s31, s50, s31
	s_and_b64 s[36:37], vcc, exec
	s_cselect_b32 s27, s31, s43
	s_cselect_b32 s41, s30, s42
	s_ashr_i32 s23, s22, 31
	s_lshl_b64 s[36:37], s[22:23], 20
	s_add_u32 s36, s51, s36
	s_addc_u32 s37, s52, s37
	s_and_b64 s[46:47], vcc, exec
	s_cselect_b32 s23, s37, s45
	s_cselect_b32 s63, s36, s44
	s_add_u32 s42, s42, 0x80080
	s_addc_u32 s43, s43, 0
	s_add_u32 s64, s44, 0x100
	s_addc_u32 s65, s45, 0
	s_mov_b32 s66, -2
	v_add_u32_e32 v248, 0x10000, v151
	ds_read_b128 v[156:159], v248
	ds_read_b128 v[160:163], v248 offset:1024
	ds_read_b128 v[180:183], v248 offset:2048
	ds_read_b128 v[184:187], v248 offset:3072
	s_add_i32 m0, s55, 0xc000
	ds_read_b128 v[188:191], v154
	ds_read_b128 v[192:195], v154 offset:1024
	ds_read_b128 v[196:199], v154 offset:2048
	ds_read_b128 v[200:203], v154 offset:3072
	ds_read_b128 v[208:211], v154 offset:4096
	ds_read_b128 v[212:215], v154 offset:5120
	ds_read_b128 v[216:219], v154 offset:6144
	ds_read_b128 v[220:223], v154 offset:7168
	global_load_lds_dwordx4 v144, s[42:43]
	s_add_i32 m0, s55, 0xe000
	s_nop 0
	global_load_lds_dwordx4 v146, s[42:43]
	s_waitcnt lgkmcnt(8)
	s_barrier
	s_setprio 1
	s_waitcnt lgkmcnt(0)
	v_mfma_f32_16x16x32_bf16 v[128:131], v[156:159], v[188:191], 0
	s_add_u32 s44, s42, 0xfff80080
	s_addc_u32 s45, s43, -1
	v_mfma_f32_16x16x32_bf16 v[124:127], v[180:183], v[188:191], 0
	s_add_i32 s67, 0, 0x10000
	v_mfma_f32_16x16x32_bf16 v[120:123], v[156:159], v[196:199], 0
	s_cmp_eq_u32 s66, 28
	s_cselect_b32 s47, s27, s45
	s_cselect_b32 s46, s41, s44
	s_cselect_b32 s45, s23, s65
	s_cselect_b32 s44, s63, s64
	v_mfma_f32_16x16x32_bf16 v[116:119], v[180:183], v[196:199], 0
	v_mfma_f32_16x16x32_bf16 v[104:107], v[156:159], v[208:211], 0
	v_mfma_f32_16x16x32_bf16 v[100:103], v[180:183], v[208:211], 0
	v_mfma_f32_16x16x32_bf16 v[88:91], v[156:159], v[216:219], 0
	v_mfma_f32_16x16x32_bf16 v[84:87], v[180:183], v[216:219], 0
	v_mfma_f32_16x16x32_bf16 v[128:131], v[160:163], v[192:195], v[128:131]
	v_mfma_f32_16x16x32_bf16 v[124:127], v[184:187], v[192:195], v[124:127]
	v_mfma_f32_16x16x32_bf16 v[120:123], v[160:163], v[200:203], v[120:123]
	v_mfma_f32_16x16x32_bf16 v[116:119], v[184:187], v[200:203], v[116:119]
	v_mfma_f32_16x16x32_bf16 v[104:107], v[160:163], v[212:215], v[104:107]
	v_mfma_f32_16x16x32_bf16 v[100:103], v[184:187], v[212:215], v[100:103]
	s_setprio 2
	s_barrier
	v_mfma_f32_16x16x32_bf16 v[88:91], v[160:163], v[220:223], v[88:91]
	v_mfma_f32_16x16x32_bf16 v[84:87], v[184:187], v[220:223], v[84:87]
	s_setprio 0
	s_add_i32 s70, 0, 0x14000
	s_add_i32 s67, s67, s54
	s_add_u32 s98, s44, 0x80
	s_addc_u32 s99, s45, 0
	s_mov_b32 m0, s67
	ds_read_b128 v[224:227], v248 offset:16384
	ds_read_b128 v[228:231], v248 offset:17408
	ds_read_b128 v[232:235], v248 offset:18432
	ds_read_b128 v[236:239], v248 offset:19456
	global_load_lds_dwordx4 v136, s[44:45]
	s_add_i32 m0, s67, 0x2000
	s_nop 0
	global_load_lds_dwordx4 v132, s[44:45]
	s_barrier
	s_setprio 1
	s_waitcnt lgkmcnt(0)
	v_mfma_f32_16x16x32_bf16 v[112:115], v[224:227], v[188:191], 0
	v_mfma_f32_16x16x32_bf16 v[108:111], v[232:235], v[188:191], 0
	v_mfma_f32_16x16x32_bf16 v[96:99], v[224:227], v[196:199], 0
	v_mfma_f32_16x16x32_bf16 v[92:95], v[232:235], v[196:199], 0
	v_mfma_f32_16x16x32_bf16 v[80:83], v[224:227], v[208:211], 0
	v_mfma_f32_16x16x32_bf16 v[76:79], v[232:235], v[208:211], 0
	v_mfma_f32_16x16x32_bf16 v[72:75], v[224:227], v[216:219], 0
	v_mfma_f32_16x16x32_bf16 v[68:71], v[232:235], v[216:219], 0
	v_mfma_f32_16x16x32_bf16 v[112:115], v[228:231], v[192:195], v[112:115]
	v_mfma_f32_16x16x32_bf16 v[108:111], v[236:239], v[192:195], v[108:111]
	v_mfma_f32_16x16x32_bf16 v[96:99], v[228:231], v[200:203], v[96:99]
	v_mfma_f32_16x16x32_bf16 v[92:95], v[236:239], v[200:203], v[92:95]
	v_mfma_f32_16x16x32_bf16 v[80:83], v[228:231], v[212:215], v[80:83]
	v_mfma_f32_16x16x32_bf16 v[76:79], v[236:239], v[212:215], v[76:79]
	s_setprio 2
	s_barrier
	v_mfma_f32_16x16x32_bf16 v[72:75], v[228:231], v[220:223], v[72:75]
	v_mfma_f32_16x16x32_bf16 v[68:71], v[236:239], v[220:223], v[68:71]
	s_setprio 0
	s_mov_b32 m0, s55
	s_add_u32 s100, s46, 0x80
	s_addc_u32 s101, s47, 0
	ds_read_b128 v[188:191], v154 offset:16384
	ds_read_b128 v[192:195], v154 offset:17408
	ds_read_b128 v[196:199], v154 offset:18432
	ds_read_b128 v[200:203], v154 offset:19456
	ds_read_b128 v[208:211], v154 offset:20480
	ds_read_b128 v[212:215], v154 offset:21504
	ds_read_b128 v[216:219], v154 offset:22528
	ds_read_b128 v[220:223], v154 offset:23552
	global_load_lds_dwordx4 v138, s[46:47]
	s_mov_b32 m0, s56
	s_nop 0
	global_load_lds_dwordx4 v134, s[46:47]
	s_waitcnt vmcnt(10)
	s_barrier
	s_setprio 1
	s_waitcnt lgkmcnt(0)
	v_mfma_f32_16x16x32_bf16 v[64:67], v[156:159], v[188:191], 0
	v_mfma_f32_16x16x32_bf16 v[60:63], v[180:183], v[188:191], 0
	v_mfma_f32_16x16x32_bf16 v[56:59], v[156:159], v[196:199], 0
	v_mfma_f32_16x16x32_bf16 v[52:55], v[180:183], v[196:199], 0
	v_mfma_f32_16x16x32_bf16 v[40:43], v[156:159], v[208:211], 0
	v_mfma_f32_16x16x32_bf16 v[36:39], v[180:183], v[208:211], 0
	v_mfma_f32_16x16x32_bf16 v[24:27], v[156:159], v[216:219], 0
	v_mfma_f32_16x16x32_bf16 v[20:23], v[180:183], v[216:219], 0
	v_mfma_f32_16x16x32_bf16 v[64:67], v[160:163], v[192:195], v[64:67]
	v_mfma_f32_16x16x32_bf16 v[60:63], v[184:187], v[192:195], v[60:63]
	v_mfma_f32_16x16x32_bf16 v[56:59], v[160:163], v[200:203], v[56:59]
	v_mfma_f32_16x16x32_bf16 v[52:55], v[184:187], v[200:203], v[52:55]
	v_mfma_f32_16x16x32_bf16 v[40:43], v[160:163], v[212:215], v[40:43]
	v_mfma_f32_16x16x32_bf16 v[36:39], v[184:187], v[212:215], v[36:39]
	s_setprio 2
	s_barrier
; #define PG8_STAGE(bufoff, gbase, voff) do { _Pragma("unroll") for (int _i = 0; _i < 2; ++_i) \
;     __builtin_amdgcn_global_load_lds((const unsigned*)((const char*)(gbase) + (voff)[_i]), (LAS unsigned*)(lds + (bufoff) + ldsw + _i * 8192), 16, 0, 0); } while (0)
; #define PG8_LDA(dst, b, h) do { _Pragma("unroll") for (int m = 0; m < 4; ++m) _Pragma("unroll") for (int k = 0; k < 2; ++k) dst[m][k] = *(const LAS bf16x8*)(lds + PG8_SA(b, h) + aoff + m * 2048 + k * 1024); } while (0)
; #define PG8_LDB(dst, b, h) do { _Pragma("unroll") for (int n = 0; n < 2; ++n) _Pragma("unroll") for (int k = 0; k < 2; ++k) dst[n][k] = *(const LAS bf16x8*)(lds + PG8_SB(b, h) + boff + n * 2048 + k * 1024); } while (0)
; #define PG8_MMA(ai, bj, At, Bt) do { __builtin_amdgcn_s_setprio(1); _Pragma("unroll") for (int m = 0; m < 4; ++m) _Pragma("unroll") for (int n = 0; n < 2; ++n) _Pragma("unroll") for (int k = 0; k < 2; ++k) \
;     acc[ai][bj][m][n] = __builtin_amdgcn_mfma_f32_16x16x32_bf16(Bt[n][k], At[m][k], acc[ai][bj][m][n], 0, 0, 0); __builtin_amdgcn_s_setprio(0); } while (0)
; #define PG8_WAIT_V(n) asm volatile("s_waitcnt vmcnt(" #n ")" ::: "memory")
; #define PG8_WAIT_L(n) asm volatile("s_waitcnt lgkmcnt(" #n ")" ::: "memory")
; #define PG8_BAR __builtin_amdgcn_s_barrier()
; #define PG8_SCHED __builtin_amdgcn_sched_barrier(0)
; template <class Epi>
; DI void gemm_phase(LAS unsigned char* lds, const Gemm g, const Epi& E) {
;     ...
;       PG8_WAIT_V(6); PG8_BAR; PG8_MMA(1, 1, At, B1); PG8_BAR;
;       PG8_LDB(B0, 1, 0); PG8_SCHED; PG8_LDA(At, 1, 0); PG8_STAGE(PG8_SA(0, 1), a2 + hstepA, voffA);
;       PG8_WAIT_L(8); PG8_BAR; PG8_WAIT_L(0); PG8_MMA(0, 0, At, B0); PG8_BAR; PG8_SCHED;
;       PG8_LDB(B1, 1, 1); PG8_STAGE(PG8_SB(1, 0), b3, voffB);
;       PG8_BAR; PG8_WAIT_L(0); PG8_MMA(0, 1, At, B1); PG8_BAR;
;       PG8_LDA(At, 1, 1); PG8_STAGE(PG8_SA(1, 0), a3, voffA);
;       PG8_BAR; PG8_WAIT_L(0); PG8_MMA(1, 0, At, B0); PG8_BAR; PG8_SCHED;
	v_mfma_f32_16x16x32_bf16 v[24:27], v[160:163], v[220:223], v[24:27]
	v_mfma_f32_16x16x32_bf16 v[20:23], v[184:187], v[220:223], v[20:23]
	s_setprio 0
	ds_read_b128 v[156:159], v248 offset:32768
	ds_read_b128 v[160:163], v248 offset:33792
	ds_read_b128 v[180:183], v248 offset:34816
	ds_read_b128 v[184:187], v248 offset:35840
	s_add_u32 s68, s44, 0x80000
	s_addc_u32 s69, s45, 0
	s_add_i32 s67, s70, s54
	s_mov_b32 m0, s67
	s_nop 0
	global_load_lds_dwordx4 v136, s[68:69]
	s_add_i32 m0, s67, 0x2000
	s_nop 0
	global_load_lds_dwordx4 v132, s[68:69]
	s_waitcnt vmcnt(6)
	s_barrier
	s_setprio 1
	v_mfma_f32_16x16x32_bf16 v[48:51], v[224:227], v[188:191], 0
	v_mfma_f32_16x16x32_bf16 v[44:47], v[232:235], v[188:191], 0
	v_mfma_f32_16x16x32_bf16 v[32:35], v[224:227], v[196:199], 0
	v_mfma_f32_16x16x32_bf16 v[28:31], v[232:235], v[196:199], 0
	v_mfma_f32_16x16x32_bf16 v[16:19], v[224:227], v[208:211], 0
	v_mfma_f32_16x16x32_bf16 v[12:15], v[232:235], v[208:211], 0
	v_mfma_f32_16x16x32_bf16 v[8:11], v[224:227], v[216:219], 0
	v_mfma_f32_16x16x32_bf16 v[4:7], v[232:235], v[216:219], 0
	v_mfma_f32_16x16x32_bf16 v[48:51], v[228:231], v[192:195], v[48:51]
	v_mfma_f32_16x16x32_bf16 v[44:47], v[236:239], v[192:195], v[44:47]
	v_mfma_f32_16x16x32_bf16 v[32:35], v[228:231], v[200:203], v[32:35]
	v_mfma_f32_16x16x32_bf16 v[28:31], v[236:239], v[200:203], v[28:31]
	v_mfma_f32_16x16x32_bf16 v[16:19], v[228:231], v[212:215], v[16:19]
	v_mfma_f32_16x16x32_bf16 v[12:15], v[236:239], v[212:215], v[12:15]
	s_setprio 2
	s_barrier
	v_mfma_f32_16x16x32_bf16 v[8:11], v[228:231], v[220:223], v[8:11]
	v_mfma_f32_16x16x32_bf16 v[4:7], v[236:239], v[220:223], v[4:7]
	s_setprio 0
	s_add_i32 s67, 0, 0x18000
	s_add_u32 s46, s46, 0x80000
	s_addc_u32 s47, s47, 0
	s_mov_b32 m0, s57
	ds_read_b128 v[188:191], v154 offset:32768
	ds_read_b128 v[192:195], v154 offset:33792
	ds_read_b128 v[196:199], v154 offset:34816
	ds_read_b128 v[200:203], v154 offset:35840
	ds_read_b128 v[208:211], v154 offset:36864
	ds_read_b128 v[212:215], v154 offset:37888
	ds_read_b128 v[216:219], v154 offset:38912
	ds_read_b128 v[220:223], v154 offset:39936
	global_load_lds_dwordx4 v138, s[46:47]
	s_mov_b32 m0, s58
	s_nop 0
	global_load_lds_dwordx4 v134, s[46:47]
	s_waitcnt lgkmcnt(8)
	s_barrier
	s_setprio 1
	s_waitcnt lgkmcnt(0)
	v_mfma_f32_16x16x32_bf16 v[128:131], v[156:159], v[188:191], v[128:131]
	v_mfma_f32_16x16x32_bf16 v[124:127], v[180:183], v[188:191], v[124:127]
	v_mfma_f32_16x16x32_bf16 v[120:123], v[156:159], v[196:199], v[120:123]
	v_mfma_f32_16x16x32_bf16 v[116:119], v[180:183], v[196:199], v[116:119]
	v_mfma_f32_16x16x32_bf16 v[104:107], v[156:159], v[208:211], v[104:107]
	v_mfma_f32_16x16x32_bf16 v[100:103], v[180:183], v[208:211], v[100:103]
	v_mfma_f32_16x16x32_bf16 v[88:91], v[156:159], v[216:219], v[88:91]
	v_mfma_f32_16x16x32_bf16 v[84:87], v[180:183], v[216:219], v[84:87]
	v_mfma_f32_16x16x32_bf16 v[128:131], v[160:163], v[192:195], v[128:131]
	v_mfma_f32_16x16x32_bf16 v[124:127], v[184:187], v[192:195], v[124:127]
	v_mfma_f32_16x16x32_bf16 v[120:123], v[160:163], v[200:203], v[120:123]
	v_mfma_f32_16x16x32_bf16 v[116:119], v[184:187], v[200:203], v[116:119]
	v_mfma_f32_16x16x32_bf16 v[104:107], v[160:163], v[212:215], v[104:107]
	v_mfma_f32_16x16x32_bf16 v[100:103], v[184:187], v[212:215], v[100:103]
	s_setprio 2
	s_barrier
	v_mfma_f32_16x16x32_bf16 v[88:91], v[160:163], v[220:223], v[88:91]
	v_mfma_f32_16x16x32_bf16 v[84:87], v[184:187], v[220:223], v[84:87]
	s_setprio 0
	s_add_i32 s46, 0, 0x1c000
	s_add_i32 s47, s67, s54
	s_mov_b32 m0, s47
	ds_read_b128 v[224:227], v248 offset:49152
	ds_read_b128 v[228:231], v248 offset:50176
	ds_read_b128 v[232:235], v248 offset:51200
	ds_read_b128 v[236:239], v248 offset:52224
	global_load_lds_dwordx4 v136, s[98:99]
	s_add_i32 m0, s47, 0x2000
	s_nop 0
	global_load_lds_dwordx4 v132, s[98:99]
	s_barrier
	s_setprio 1
	s_waitcnt lgkmcnt(0)
	v_mfma_f32_16x16x32_bf16 v[112:115], v[224:227], v[188:191], v[112:115]
	v_mfma_f32_16x16x32_bf16 v[108:111], v[232:235], v[188:191], v[108:111]
	v_mfma_f32_16x16x32_bf16 v[96:99], v[224:227], v[196:199], v[96:99]
	v_mfma_f32_16x16x32_bf16 v[92:95], v[232:235], v[196:199], v[92:95]
	v_mfma_f32_16x16x32_bf16 v[80:83], v[224:227], v[208:211], v[80:83]
	v_mfma_f32_16x16x32_bf16 v[76:79], v[232:235], v[208:211], v[76:79]
	v_mfma_f32_16x16x32_bf16 v[72:75], v[224:227], v[216:219], v[72:75]
	v_mfma_f32_16x16x32_bf16 v[68:71], v[232:235], v[216:219], v[68:71]
	v_mfma_f32_16x16x32_bf16 v[112:115], v[228:231], v[192:195], v[112:115]
	v_mfma_f32_16x16x32_bf16 v[108:111], v[236:239], v[192:195], v[108:111]
	v_mfma_f32_16x16x32_bf16 v[96:99], v[228:231], v[200:203], v[96:99]
	v_mfma_f32_16x16x32_bf16 v[92:95], v[236:239], v[200:203], v[92:95]
	v_mfma_f32_16x16x32_bf16 v[80:83], v[228:231], v[212:215], v[80:83]
	v_mfma_f32_16x16x32_bf16 v[76:79], v[236:239], v[212:215], v[76:79]
	s_setprio 2
	s_barrier
	v_mfma_f32_16x16x32_bf16 v[72:75], v[228:231], v[220:223], v[72:75]
	v_mfma_f32_16x16x32_bf16 v[68:71], v[236:239], v[220:223], v[68:71]
	s_setprio 0
	s_mov_b32 m0, s60
	ds_read_b128 v[188:191], v154 offset:49152
	ds_read_b128 v[192:195], v154 offset:50176
	ds_read_b128 v[196:199], v154 offset:51200
	ds_read_b128 v[200:203], v154 offset:52224
	ds_read_b128 v[208:211], v154 offset:53248
	ds_read_b128 v[212:215], v154 offset:54272
	ds_read_b128 v[216:219], v154 offset:55296
	ds_read_b128 v[220:223], v154 offset:56320
	global_load_lds_dwordx4 v138, s[100:101]
	s_mov_b32 m0, s61
	s_nop 0
	global_load_lds_dwordx4 v134, s[100:101]
	s_waitcnt vmcnt(10)
	s_barrier
; #define PG8_STAGE(bufoff, gbase, voff) do { _Pragma("unroll") for (int _i = 0; _i < 2; ++_i) \
;     __builtin_amdgcn_global_load_lds((const unsigned*)((const char*)(gbase) + (voff)[_i]), (LAS unsigned*)(lds + (bufoff) + ldsw + _i * 8192), 16, 0, 0); } while (0)
; #define PG8_LDA(dst, b, h) do { _Pragma("unroll") for (int m = 0; m < 4; ++m) _Pragma("unroll") for (int k = 0; k < 2; ++k) dst[m][k] = *(const LAS bf16x8*)(lds + PG8_SA(b, h) + aoff + m * 2048 + k * 1024); } while (0)
; #define PG8_LDB(dst, b, h) do { _Pragma("unroll") for (int n = 0; n < 2; ++n) _Pragma("unroll") for (int k = 0; k < 2; ++k) dst[n][k] = *(const LAS bf16x8*)(lds + PG8_SB(b, h) + boff + n * 2048 + k * 1024); } while (0)
; #define PG8_MMA(ai, bj, At, Bt) do { __builtin_amdgcn_s_setprio(1); _Pragma("unroll") for (int m = 0; m < 4; ++m) _Pragma("unroll") for (int n = 0; n < 2; ++n) _Pragma("unroll") for (int k = 0; k < 2; ++k) \
;     acc[ai][bj][m][n] = __builtin_amdgcn_mfma_f32_16x16x32_bf16(Bt[n][k], At[m][k], acc[ai][bj][m][n], 0, 0, 0); __builtin_amdgcn_s_setprio(0); } while (0)
; #define PG8_WAIT_V(n) asm volatile("s_waitcnt vmcnt(" #n ")" ::: "memory")
; #define PG8_WAIT_L(n) asm volatile("s_waitcnt lgkmcnt(" #n ")" ::: "memory")
; #define PG8_BAR __builtin_amdgcn_s_barrier()
; template <class Epi>
; DI void gemm_phase(LAS unsigned char* lds, const Gemm g, const Epi& E) {
;     ...
;     const bool has_next = S.next(ui + 1, nxt);
;     const char* nA = has_next ? PG8_APTR(nxt) : cA; const char* nB = has_next ? (const char*)g.Bt + (size_t)nxt.pn * tstepB : cB;
;     for (int t = 0; t < nt; t += 2) {
;       const bool last = (t == nt - 2);
;       const char* a1 = cA + (size_t)(t + 1) * kstep;
;       const char* a2 = last ? nA : cA + (size_t)(t + 2) * kstep; const char* b2 = last ? nB : cB + (size_t)(t + 2) * kstep;
;       const char* a3 = a2 + kstep; const char* b3 = b2 + kstep;
;       PG8_LDB(B0, 0, 0); PG8_SCHED; PG8_LDA(At, 0, 0); PG8_STAGE(PG8_SA(1, 1), a1 + hstepA, voffA);
;       PG8_WAIT_L(8); PG8_BAR; PG8_WAIT_L(0); PG8_MMA(0, 0, At, B0); PG8_BAR; PG8_SCHED;
;       PG8_LDB(B1, 0, 1); PG8_STAGE(PG8_SB(0, 0), b2, voffB);
;       PG8_BAR; PG8_WAIT_L(0); PG8_MMA(0, 1, At, B1); PG8_BAR;
;     ...
;       PG8_BAR; PG8_WAIT_L(0); PG8_MMA(1, 0, At, B0); PG8_BAR; PG8_SCHED;
;       PG8_STAGE(PG8_SB(1, 1), b3 + hstepB, voffB);
;       PG8_WAIT_V(6); PG8_BAR; PG8_MMA(1, 1, At, B1); PG8_BAR;
	s_setprio 1
	s_waitcnt lgkmcnt(0)
	v_mfma_f32_16x16x32_bf16 v[64:67], v[156:159], v[188:191], v[64:67]
	v_mfma_f32_16x16x32_bf16 v[60:63], v[180:183], v[188:191], v[60:63]
	v_mfma_f32_16x16x32_bf16 v[56:59], v[156:159], v[196:199], v[56:59]
	v_mfma_f32_16x16x32_bf16 v[52:55], v[180:183], v[196:199], v[52:55]
	v_mfma_f32_16x16x32_bf16 v[40:43], v[156:159], v[208:211], v[40:43]
	v_mfma_f32_16x16x32_bf16 v[36:39], v[180:183], v[208:211], v[36:39]
	v_mfma_f32_16x16x32_bf16 v[24:27], v[156:159], v[216:219], v[24:27]
	v_mfma_f32_16x16x32_bf16 v[20:23], v[180:183], v[216:219], v[20:23]
	v_mfma_f32_16x16x32_bf16 v[64:67], v[160:163], v[192:195], v[64:67]
	v_mfma_f32_16x16x32_bf16 v[60:63], v[184:187], v[192:195], v[60:63]
	v_mfma_f32_16x16x32_bf16 v[56:59], v[160:163], v[200:203], v[56:59]
	v_mfma_f32_16x16x32_bf16 v[52:55], v[184:187], v[200:203], v[52:55]
	v_mfma_f32_16x16x32_bf16 v[40:43], v[160:163], v[212:215], v[40:43]
	v_mfma_f32_16x16x32_bf16 v[36:39], v[184:187], v[212:215], v[36:39]
	s_setprio 2
	s_barrier
	v_mfma_f32_16x16x32_bf16 v[24:27], v[160:163], v[220:223], v[24:27]
	v_mfma_f32_16x16x32_bf16 v[20:23], v[184:187], v[220:223], v[20:23]
	s_setprio 0
	ds_read_b128 v[156:159], v248
	ds_read_b128 v[160:163], v248 offset:1024
	ds_read_b128 v[180:183], v248 offset:2048
	ds_read_b128 v[184:187], v248 offset:3072
	s_add_u32 s44, s44, 0x80080
	s_addc_u32 s45, s45, 0
	s_add_i32 s46, s46, s54
	s_mov_b32 m0, s46
	s_nop 0
	global_load_lds_dwordx4 v136, s[44:45]
	s_add_i32 m0, s46, 0x2000
	s_nop 0
	global_load_lds_dwordx4 v132, s[44:45]
	s_waitcnt vmcnt(6)
	s_barrier
	s_setprio 1
	v_mfma_f32_16x16x32_bf16 v[48:51], v[224:227], v[188:191], v[48:51]
	v_mfma_f32_16x16x32_bf16 v[44:47], v[232:235], v[188:191], v[44:47]
	v_mfma_f32_16x16x32_bf16 v[32:35], v[224:227], v[196:199], v[32:35]
	v_mfma_f32_16x16x32_bf16 v[28:31], v[232:235], v[196:199], v[28:31]
	v_mfma_f32_16x16x32_bf16 v[16:19], v[224:227], v[208:211], v[16:19]
	v_mfma_f32_16x16x32_bf16 v[12:15], v[232:235], v[208:211], v[12:15]
	v_mfma_f32_16x16x32_bf16 v[8:11], v[224:227], v[216:219], v[8:11]
	v_mfma_f32_16x16x32_bf16 v[4:7], v[232:235], v[216:219], v[4:7]
	v_mfma_f32_16x16x32_bf16 v[48:51], v[228:231], v[192:195], v[48:51]
	v_mfma_f32_16x16x32_bf16 v[44:47], v[236:239], v[192:195], v[44:47]
	v_mfma_f32_16x16x32_bf16 v[32:35], v[228:231], v[200:203], v[32:35]
	v_mfma_f32_16x16x32_bf16 v[28:31], v[236:239], v[200:203], v[28:31]
	v_mfma_f32_16x16x32_bf16 v[16:19], v[228:231], v[212:215], v[16:19]
	v_mfma_f32_16x16x32_bf16 v[12:15], v[236:239], v[212:215], v[12:15]
	s_setprio 2
	s_barrier
	v_mfma_f32_16x16x32_bf16 v[8:11], v[228:231], v[220:223], v[8:11]
	v_mfma_f32_16x16x32_bf16 v[4:7], v[236:239], v[220:223], v[4:7]
	s_setprio 0
	s_add_i32 s66, s66, 2
	s_add_u32 s42, s42, 0x100
	s_addc_u32 s43, s43, 0
	s_add_u32 s64, s64, 0x100
	s_addc_u32 s65, s65, 0
	s_cmp_gt_u32 s66, 29
	s_cbranch_scc1 .Lpeel_exit_225
.LBB0_225:
	s_add_i32 m0, s55, 0xc000
	ds_read_b128 v[188:191], v154
	ds_read_b128 v[192:195], v154 offset:1024
	ds_read_b128 v[196:199], v154 offset:2048
	ds_read_b128 v[200:203], v154 offset:3072
	ds_read_b128 v[208:211], v154 offset:4096
	ds_read_b128 v[212:215], v154 offset:5120
	ds_read_b128 v[216:219], v154 offset:6144
	ds_read_b128 v[220:223], v154 offset:7168
	global_load_lds_dwordx4 v144, s[42:43]
	s_add_i32 m0, s55, 0xe000
	s_nop 0
	global_load_lds_dwordx4 v146, s[42:43]
	s_waitcnt lgkmcnt(8)
	s_barrier
	s_setprio 1
	s_waitcnt lgkmcnt(0)
	v_mfma_f32_16x16x32_bf16 v[128:131], v[156:159], v[188:191], v[128:131]
	s_add_u32 s44, s42, 0xfff80080
	s_addc_u32 s45, s43, -1
	v_mfma_f32_16x16x32_bf16 v[124:127], v[180:183], v[188:191], v[124:127]
	s_add_i32 s67, 0, 0x10000
	v_mfma_f32_16x16x32_bf16 v[120:123], v[156:159], v[196:199], v[120:123]
	s_cmp_eq_u32 s66, 28
	s_cselect_b32 s47, s27, s45
	s_cselect_b32 s46, s41, s44
	s_cselect_b32 s45, s23, s65
	s_cselect_b32 s44, s63, s64
	v_mfma_f32_16x16x32_bf16 v[116:119], v[180:183], v[196:199], v[116:119]
	v_mfma_f32_16x16x32_bf16 v[104:107], v[156:159], v[208:211], v[104:107]
	v_mfma_f32_16x16x32_bf16 v[100:103], v[180:183], v[208:211], v[100:103]
	v_mfma_f32_16x16x32_bf16 v[88:91], v[156:159], v[216:219], v[88:91]
	v_mfma_f32_16x16x32_bf16 v[84:87], v[180:183], v[216:219], v[84:87]
	v_mfma_f32_16x16x32_bf16 v[128:131], v[160:163], v[192:195], v[128:131]
	v_mfma_f32_16x16x32_bf16 v[124:127], v[184:187], v[192:195], v[124:127]
	v_mfma_f32_16x16x32_bf16 v[120:123], v[160:163], v[200:203], v[120:123]
	v_mfma_f32_16x16x32_bf16 v[116:119], v[184:187], v[200:203], v[116:119]
	v_mfma_f32_16x16x32_bf16 v[104:107], v[160:163], v[212:215], v[104:107]
	v_mfma_f32_16x16x32_bf16 v[100:103], v[184:187], v[212:215], v[100:103]
	s_setprio 2
	s_barrier
	v_mfma_f32_16x16x32_bf16 v[88:91], v[160:163], v[220:223], v[88:91]
	v_mfma_f32_16x16x32_bf16 v[84:87], v[184:187], v[220:223], v[84:87]
	s_setprio 0
	s_add_i32 s70, 0, 0x14000
	s_add_i32 s67, s67, s54
	s_add_u32 s98, s44, 0x80
	s_addc_u32 s99, s45, 0
	s_mov_b32 m0, s67
	ds_read_b128 v[224:227], v248 offset:16384
	ds_read_b128 v[228:231], v248 offset:17408
	ds_read_b128 v[232:235], v248 offset:18432
	ds_read_b128 v[236:239], v248 offset:19456
	global_load_lds_dwordx4 v136, s[44:45]
	s_add_i32 m0, s67, 0x2000
	s_nop 0
	global_load_lds_dwordx4 v132, s[44:45]
	s_barrier
; #define PG8_STAGE(bufoff, gbase, voff) do { _Pragma("unroll") for (int _i = 0; _i < 2; ++_i) \
;     __builtin_amdgcn_global_load_lds((const unsigned*)((const char*)(gbase) + (voff)[_i]), (LAS unsigned*)(lds + (bufoff) + ldsw + _i * 8192), 16, 0, 0); } while (0)
; #define PG8_LDA(dst, b, h) do { _Pragma("unroll") for (int m = 0; m < 4; ++m) _Pragma("unroll") for (int k = 0; k < 2; ++k) dst[m][k] = *(const LAS bf16x8*)(lds + PG8_SA(b, h) + aoff + m * 2048 + k * 1024); } while (0)
; #define PG8_LDB(dst, b, h) do { _Pragma("unroll") for (int n = 0; n < 2; ++n) _Pragma("unroll") for (int k = 0; k < 2; ++k) dst[n][k] = *(const LAS bf16x8*)(lds + PG8_SB(b, h) + boff + n * 2048 + k * 1024); } while (0)
; #define PG8_MMA(ai, bj, At, Bt) do { __builtin_amdgcn_s_setprio(1); _Pragma("unroll") for (int m = 0; m < 4; ++m) _Pragma("unroll") for (int n = 0; n < 2; ++n) _Pragma("unroll") for (int k = 0; k < 2; ++k) \
;     acc[ai][bj][m][n] = __builtin_amdgcn_mfma_f32_16x16x32_bf16(Bt[n][k], At[m][k], acc[ai][bj][m][n], 0, 0, 0); __builtin_amdgcn_s_setprio(0); } while (0)
; #define PG8_WAIT_V(n) asm volatile("s_waitcnt vmcnt(" #n ")" ::: "memory")
; #define PG8_WAIT_L(n) asm volatile("s_waitcnt lgkmcnt(" #n ")" ::: "memory")
; #define PG8_BAR __builtin_amdgcn_s_barrier()
; #define PG8_SCHED __builtin_amdgcn_sched_barrier(0)
; template <class Epi>
; DI void gemm_phase(LAS unsigned char* lds, const Gemm g, const Epi& E) {
;     ...
;       PG8_BAR; PG8_WAIT_L(0); PG8_MMA(0, 1, At, B1); PG8_BAR;
;       PG8_LDA(At, 0, 1); PG8_STAGE(PG8_SA(0, 0), a2, voffA);
;       PG8_BAR; PG8_WAIT_L(0); PG8_MMA(1, 0, At, B0); PG8_BAR; PG8_SCHED;
;       PG8_STAGE(PG8_SB(0, 1), b2 + hstepB, voffB);
;       PG8_WAIT_V(6); PG8_BAR; PG8_MMA(1, 1, At, B1); PG8_BAR;
;       PG8_LDB(B0, 1, 0); PG8_SCHED; PG8_LDA(At, 1, 0); PG8_STAGE(PG8_SA(0, 1), a2 + hstepA, voffA);
;       PG8_WAIT_L(8); PG8_BAR; PG8_WAIT_L(0); PG8_MMA(0, 0, At, B0); PG8_BAR; PG8_SCHED;
;       PG8_LDB(B1, 1, 1); PG8_STAGE(PG8_SB(1, 0), b3, voffB);
;       PG8_BAR; PG8_WAIT_L(0); PG8_MMA(0, 1, At, B1); PG8_BAR;
	s_setprio 1
	s_waitcnt lgkmcnt(0)
	v_mfma_f32_16x16x32_bf16 v[112:115], v[224:227], v[188:191], v[112:115]
	v_mfma_f32_16x16x32_bf16 v[108:111], v[232:235], v[188:191], v[108:111]
	v_mfma_f32_16x16x32_bf16 v[96:99], v[224:227], v[196:199], v[96:99]
	v_mfma_f32_16x16x32_bf16 v[92:95], v[232:235], v[196:199], v[92:95]
	v_mfma_f32_16x16x32_bf16 v[80:83], v[224:227], v[208:211], v[80:83]
	v_mfma_f32_16x16x32_bf16 v[76:79], v[232:235], v[208:211], v[76:79]
	v_mfma_f32_16x16x32_bf16 v[72:75], v[224:227], v[216:219], v[72:75]
	v_mfma_f32_16x16x32_bf16 v[68:71], v[232:235], v[216:219], v[68:71]
	v_mfma_f32_16x16x32_bf16 v[112:115], v[228:231], v[192:195], v[112:115]
	v_mfma_f32_16x16x32_bf16 v[108:111], v[236:239], v[192:195], v[108:111]
	v_mfma_f32_16x16x32_bf16 v[96:99], v[228:231], v[200:203], v[96:99]
	v_mfma_f32_16x16x32_bf16 v[92:95], v[236:239], v[200:203], v[92:95]
	v_mfma_f32_16x16x32_bf16 v[80:83], v[228:231], v[212:215], v[80:83]
	v_mfma_f32_16x16x32_bf16 v[76:79], v[236:239], v[212:215], v[76:79]
	s_setprio 2
	s_barrier
	v_mfma_f32_16x16x32_bf16 v[72:75], v[228:231], v[220:223], v[72:75]
	v_mfma_f32_16x16x32_bf16 v[68:71], v[236:239], v[220:223], v[68:71]
	s_setprio 0
	s_mov_b32 m0, s55
	s_add_u32 s100, s46, 0x80
	s_addc_u32 s101, s47, 0
	ds_read_b128 v[188:191], v154 offset:16384
	ds_read_b128 v[192:195], v154 offset:17408
	ds_read_b128 v[196:199], v154 offset:18432
	ds_read_b128 v[200:203], v154 offset:19456
	ds_read_b128 v[208:211], v154 offset:20480
	ds_read_b128 v[212:215], v154 offset:21504
	ds_read_b128 v[216:219], v154 offset:22528
	ds_read_b128 v[220:223], v154 offset:23552
	global_load_lds_dwordx4 v138, s[46:47]
	s_mov_b32 m0, s56
	s_nop 0
	global_load_lds_dwordx4 v134, s[46:47]
	s_waitcnt vmcnt(10)
	s_barrier
	s_setprio 1
	s_waitcnt lgkmcnt(0)
	v_mfma_f32_16x16x32_bf16 v[64:67], v[156:159], v[188:191], v[64:67]
	v_mfma_f32_16x16x32_bf16 v[60:63], v[180:183], v[188:191], v[60:63]
	v_mfma_f32_16x16x32_bf16 v[56:59], v[156:159], v[196:199], v[56:59]
	v_mfma_f32_16x16x32_bf16 v[52:55], v[180:183], v[196:199], v[52:55]
	v_mfma_f32_16x16x32_bf16 v[40:43], v[156:159], v[208:211], v[40:43]
	v_mfma_f32_16x16x32_bf16 v[36:39], v[180:183], v[208:211], v[36:39]
	v_mfma_f32_16x16x32_bf16 v[24:27], v[156:159], v[216:219], v[24:27]
	v_mfma_f32_16x16x32_bf16 v[20:23], v[180:183], v[216:219], v[20:23]
	v_mfma_f32_16x16x32_bf16 v[64:67], v[160:163], v[192:195], v[64:67]
	v_mfma_f32_16x16x32_bf16 v[60:63], v[184:187], v[192:195], v[60:63]
	v_mfma_f32_16x16x32_bf16 v[56:59], v[160:163], v[200:203], v[56:59]
	v_mfma_f32_16x16x32_bf16 v[52:55], v[184:187], v[200:203], v[52:55]
	v_mfma_f32_16x16x32_bf16 v[40:43], v[160:163], v[212:215], v[40:43]
	v_mfma_f32_16x16x32_bf16 v[36:39], v[184:187], v[212:215], v[36:39]
	s_setprio 2
	s_barrier
	v_mfma_f32_16x16x32_bf16 v[24:27], v[160:163], v[220:223], v[24:27]
	v_mfma_f32_16x16x32_bf16 v[20:23], v[184:187], v[220:223], v[20:23]
	s_setprio 0
	ds_read_b128 v[156:159], v248 offset:32768
	ds_read_b128 v[160:163], v248 offset:33792
	ds_read_b128 v[180:183], v248 offset:34816
	ds_read_b128 v[184:187], v248 offset:35840
	s_add_u32 s68, s44, 0x80000
	s_addc_u32 s69, s45, 0
	s_add_i32 s67, s70, s54
	s_mov_b32 m0, s67
	s_nop 0
	global_load_lds_dwordx4 v136, s[68:69]
	s_add_i32 m0, s67, 0x2000
	s_nop 0
	global_load_lds_dwordx4 v132, s[68:69]
	s_waitcnt vmcnt(6)
	s_barrier
	s_setprio 1
	v_mfma_f32_16x16x32_bf16 v[48:51], v[224:227], v[188:191], v[48:51]
	v_mfma_f32_16x16x32_bf16 v[44:47], v[232:235], v[188:191], v[44:47]
	v_mfma_f32_16x16x32_bf16 v[32:35], v[224:227], v[196:199], v[32:35]
	v_mfma_f32_16x16x32_bf16 v[28:31], v[232:235], v[196:199], v[28:31]
	v_mfma_f32_16x16x32_bf16 v[16:19], v[224:227], v[208:211], v[16:19]
	v_mfma_f32_16x16x32_bf16 v[12:15], v[232:235], v[208:211], v[12:15]
	v_mfma_f32_16x16x32_bf16 v[8:11], v[224:227], v[216:219], v[8:11]
	v_mfma_f32_16x16x32_bf16 v[4:7], v[232:235], v[216:219], v[4:7]
	v_mfma_f32_16x16x32_bf16 v[48:51], v[228:231], v[192:195], v[48:51]
	v_mfma_f32_16x16x32_bf16 v[44:47], v[236:239], v[192:195], v[44:47]
	v_mfma_f32_16x16x32_bf16 v[32:35], v[228:231], v[200:203], v[32:35]
	v_mfma_f32_16x16x32_bf16 v[28:31], v[236:239], v[200:203], v[28:31]
	v_mfma_f32_16x16x32_bf16 v[16:19], v[228:231], v[212:215], v[16:19]
	v_mfma_f32_16x16x32_bf16 v[12:15], v[236:239], v[212:215], v[12:15]
	s_setprio 2
	s_barrier
	v_mfma_f32_16x16x32_bf16 v[8:11], v[228:231], v[220:223], v[8:11]
	v_mfma_f32_16x16x32_bf16 v[4:7], v[236:239], v[220:223], v[4:7]
	s_setprio 0
	s_add_i32 s67, 0, 0x18000
	s_add_u32 s46, s46, 0x80000
	s_addc_u32 s47, s47, 0
	s_mov_b32 m0, s57
	ds_read_b128 v[188:191], v154 offset:32768
	ds_read_b128 v[192:195], v154 offset:33792
	ds_read_b128 v[196:199], v154 offset:34816
	ds_read_b128 v[200:203], v154 offset:35840
	ds_read_b128 v[208:211], v154 offset:36864
	ds_read_b128 v[212:215], v154 offset:37888
	ds_read_b128 v[216:219], v154 offset:38912
	ds_read_b128 v[220:223], v154 offset:39936
	global_load_lds_dwordx4 v138, s[46:47]
	s_mov_b32 m0, s58
	s_nop 0
	global_load_lds_dwordx4 v134, s[46:47]
	s_waitcnt lgkmcnt(8)
	s_barrier
	s_setprio 1
	s_waitcnt lgkmcnt(0)
	v_mfma_f32_16x16x32_bf16 v[128:131], v[156:159], v[188:191], v[128:131]
	v_mfma_f32_16x16x32_bf16 v[124:127], v[180:183], v[188:191], v[124:127]
	v_mfma_f32_16x16x32_bf16 v[120:123], v[156:159], v[196:199], v[120:123]
	v_mfma_f32_16x16x32_bf16 v[116:119], v[180:183], v[196:199], v[116:119]
	v_mfma_f32_16x16x32_bf16 v[104:107], v[156:159], v[208:211], v[104:107]
	v_mfma_f32_16x16x32_bf16 v[100:103], v[180:183], v[208:211], v[100:103]
	v_mfma_f32_16x16x32_bf16 v[88:91], v[156:159], v[216:219], v[88:91]
	v_mfma_f32_16x16x32_bf16 v[84:87], v[180:183], v[216:219], v[84:87]
	v_mfma_f32_16x16x32_bf16 v[128:131], v[160:163], v[192:195], v[128:131]
	v_mfma_f32_16x16x32_bf16 v[124:127], v[184:187], v[192:195], v[124:127]
	v_mfma_f32_16x16x32_bf16 v[120:123], v[160:163], v[200:203], v[120:123]
	v_mfma_f32_16x16x32_bf16 v[116:119], v[184:187], v[200:203], v[116:119]
	v_mfma_f32_16x16x32_bf16 v[104:107], v[160:163], v[212:215], v[104:107]
	v_mfma_f32_16x16x32_bf16 v[100:103], v[184:187], v[212:215], v[100:103]
	s_setprio 2
	s_barrier
; #define PG8_STAGE(bufoff, gbase, voff) do { _Pragma("unroll") for (int _i = 0; _i < 2; ++_i) \
;     __builtin_amdgcn_global_load_lds((const unsigned*)((const char*)(gbase) + (voff)[_i]), (LAS unsigned*)(lds + (bufoff) + ldsw + _i * 8192), 16, 0, 0); } while (0)
; #define PG8_LDA(dst, b, h) do { _Pragma("unroll") for (int m = 0; m < 4; ++m) _Pragma("unroll") for (int k = 0; k < 2; ++k) dst[m][k] = *(const LAS bf16x8*)(lds + PG8_SA(b, h) + aoff + m * 2048 + k * 1024); } while (0)
; #define PG8_MMA(ai, bj, At, Bt) do { __builtin_amdgcn_s_setprio(1); _Pragma("unroll") for (int m = 0; m < 4; ++m) _Pragma("unroll") for (int n = 0; n < 2; ++n) _Pragma("unroll") for (int k = 0; k < 2; ++k) \
;     acc[ai][bj][m][n] = __builtin_amdgcn_mfma_f32_16x16x32_bf16(Bt[n][k], At[m][k], acc[ai][bj][m][n], 0, 0, 0); __builtin_amdgcn_s_setprio(0); } while (0)
; #define PG8_WAIT_V(n) asm volatile("s_waitcnt vmcnt(" #n ")" ::: "memory")
; #define PG8_WAIT_L(n) asm volatile("s_waitcnt lgkmcnt(" #n ")" ::: "memory")
; #define PG8_BAR __builtin_amdgcn_s_barrier()
; #define PG8_SCHED __builtin_amdgcn_sched_barrier(0)
; template <class Epi>
; DI void gemm_phase(LAS unsigned char* lds, const Gemm g, const Epi& E) {
;     ...
;       PG8_BAR; PG8_WAIT_L(0); PG8_MMA(0, 1, At, B1); PG8_BAR;
;       PG8_LDA(At, 1, 1); PG8_STAGE(PG8_SA(1, 0), a3, voffA);
;       PG8_BAR; PG8_WAIT_L(0); PG8_MMA(1, 0, At, B0); PG8_BAR; PG8_SCHED;
;       PG8_STAGE(PG8_SB(1, 1), b3 + hstepB, voffB);
;       PG8_WAIT_V(6); PG8_BAR; PG8_MMA(1, 1, At, B1); PG8_BAR;
	v_mfma_f32_16x16x32_bf16 v[88:91], v[160:163], v[220:223], v[88:91]
	v_mfma_f32_16x16x32_bf16 v[84:87], v[184:187], v[220:223], v[84:87]
	s_setprio 0
	s_add_i32 s46, 0, 0x1c000
	s_add_i32 s47, s67, s54
	s_mov_b32 m0, s47
	ds_read_b128 v[224:227], v248 offset:49152
	ds_read_b128 v[228:231], v248 offset:50176
	ds_read_b128 v[232:235], v248 offset:51200
	ds_read_b128 v[236:239], v248 offset:52224
	global_load_lds_dwordx4 v136, s[98:99]
	s_add_i32 m0, s47, 0x2000
	s_nop 0
	global_load_lds_dwordx4 v132, s[98:99]
	s_barrier
	s_setprio 1
	s_waitcnt lgkmcnt(0)
	v_mfma_f32_16x16x32_bf16 v[112:115], v[224:227], v[188:191], v[112:115]
	v_mfma_f32_16x16x32_bf16 v[108:111], v[232:235], v[188:191], v[108:111]
	v_mfma_f32_16x16x32_bf16 v[96:99], v[224:227], v[196:199], v[96:99]
	v_mfma_f32_16x16x32_bf16 v[92:95], v[232:235], v[196:199], v[92:95]
	v_mfma_f32_16x16x32_bf16 v[80:83], v[224:227], v[208:211], v[80:83]
	v_mfma_f32_16x16x32_bf16 v[76:79], v[232:235], v[208:211], v[76:79]
	v_mfma_f32_16x16x32_bf16 v[72:75], v[224:227], v[216:219], v[72:75]
	v_mfma_f32_16x16x32_bf16 v[68:71], v[232:235], v[216:219], v[68:71]
	v_mfma_f32_16x16x32_bf16 v[112:115], v[228:231], v[192:195], v[112:115]
	v_mfma_f32_16x16x32_bf16 v[108:111], v[236:239], v[192:195], v[108:111]
	v_mfma_f32_16x16x32_bf16 v[96:99], v[228:231], v[200:203], v[96:99]
	v_mfma_f32_16x16x32_bf16 v[92:95], v[236:239], v[200:203], v[92:95]
	v_mfma_f32_16x16x32_bf16 v[80:83], v[228:231], v[212:215], v[80:83]
	v_mfma_f32_16x16x32_bf16 v[76:79], v[236:239], v[212:215], v[76:79]
	s_setprio 2
	s_barrier
	v_mfma_f32_16x16x32_bf16 v[72:75], v[228:231], v[220:223], v[72:75]
	v_mfma_f32_16x16x32_bf16 v[68:71], v[236:239], v[220:223], v[68:71]
	s_setprio 0
	s_mov_b32 m0, s60
	ds_read_b128 v[188:191], v154 offset:49152
	ds_read_b128 v[192:195], v154 offset:50176
	ds_read_b128 v[196:199], v154 offset:51200
	ds_read_b128 v[200:203], v154 offset:52224
	ds_read_b128 v[208:211], v154 offset:53248
	ds_read_b128 v[212:215], v154 offset:54272
	ds_read_b128 v[216:219], v154 offset:55296
	ds_read_b128 v[220:223], v154 offset:56320
	global_load_lds_dwordx4 v138, s[100:101]
	s_mov_b32 m0, s61
	s_nop 0
	global_load_lds_dwordx4 v134, s[100:101]
	s_waitcnt vmcnt(10)
	s_barrier
	s_setprio 1
	s_waitcnt lgkmcnt(0)
	v_mfma_f32_16x16x32_bf16 v[64:67], v[156:159], v[188:191], v[64:67]
	v_mfma_f32_16x16x32_bf16 v[60:63], v[180:183], v[188:191], v[60:63]
	v_mfma_f32_16x16x32_bf16 v[56:59], v[156:159], v[196:199], v[56:59]
	v_mfma_f32_16x16x32_bf16 v[52:55], v[180:183], v[196:199], v[52:55]
	v_mfma_f32_16x16x32_bf16 v[40:43], v[156:159], v[208:211], v[40:43]
	v_mfma_f32_16x16x32_bf16 v[36:39], v[180:183], v[208:211], v[36:39]
	v_mfma_f32_16x16x32_bf16 v[24:27], v[156:159], v[216:219], v[24:27]
	v_mfma_f32_16x16x32_bf16 v[20:23], v[180:183], v[216:219], v[20:23]
	v_mfma_f32_16x16x32_bf16 v[64:67], v[160:163], v[192:195], v[64:67]
	v_mfma_f32_16x16x32_bf16 v[60:63], v[184:187], v[192:195], v[60:63]
	v_mfma_f32_16x16x32_bf16 v[56:59], v[160:163], v[200:203], v[56:59]
	v_mfma_f32_16x16x32_bf16 v[52:55], v[184:187], v[200:203], v[52:55]
	v_mfma_f32_16x16x32_bf16 v[40:43], v[160:163], v[212:215], v[40:43]
	v_mfma_f32_16x16x32_bf16 v[36:39], v[184:187], v[212:215], v[36:39]
	s_setprio 2
	s_barrier
	v_mfma_f32_16x16x32_bf16 v[24:27], v[160:163], v[220:223], v[24:27]
	v_mfma_f32_16x16x32_bf16 v[20:23], v[184:187], v[220:223], v[20:23]
	s_setprio 0
	ds_read_b128 v[156:159], v248
	ds_read_b128 v[160:163], v248 offset:1024
	ds_read_b128 v[180:183], v248 offset:2048
	ds_read_b128 v[184:187], v248 offset:3072
	s_add_u32 s44, s44, 0x80080
	s_addc_u32 s45, s45, 0
	s_add_i32 s46, s46, s54
	s_mov_b32 m0, s46
	s_nop 0
	global_load_lds_dwordx4 v136, s[44:45]
	s_add_i32 m0, s46, 0x2000
	s_nop 0
	global_load_lds_dwordx4 v132, s[44:45]
	s_waitcnt vmcnt(6)
	s_barrier
	s_setprio 1
	v_mfma_f32_16x16x32_bf16 v[48:51], v[224:227], v[188:191], v[48:51]
	v_mfma_f32_16x16x32_bf16 v[44:47], v[232:235], v[188:191], v[44:47]
	v_mfma_f32_16x16x32_bf16 v[32:35], v[224:227], v[196:199], v[32:35]
	v_mfma_f32_16x16x32_bf16 v[28:31], v[232:235], v[196:199], v[28:31]
	v_mfma_f32_16x16x32_bf16 v[16:19], v[224:227], v[208:211], v[16:19]
	v_mfma_f32_16x16x32_bf16 v[12:15], v[232:235], v[208:211], v[12:15]
	v_mfma_f32_16x16x32_bf16 v[8:11], v[224:227], v[216:219], v[8:11]
	v_mfma_f32_16x16x32_bf16 v[4:7], v[232:235], v[216:219], v[4:7]
	v_mfma_f32_16x16x32_bf16 v[48:51], v[228:231], v[192:195], v[48:51]
	v_mfma_f32_16x16x32_bf16 v[44:47], v[236:239], v[192:195], v[44:47]
	v_mfma_f32_16x16x32_bf16 v[32:35], v[228:231], v[200:203], v[32:35]
	v_mfma_f32_16x16x32_bf16 v[28:31], v[236:239], v[200:203], v[28:31]
	v_mfma_f32_16x16x32_bf16 v[16:19], v[228:231], v[212:215], v[16:19]
	v_mfma_f32_16x16x32_bf16 v[12:15], v[236:239], v[212:215], v[12:15]
	s_setprio 2
	s_barrier
	v_mfma_f32_16x16x32_bf16 v[8:11], v[228:231], v[220:223], v[8:11]
	v_mfma_f32_16x16x32_bf16 v[4:7], v[236:239], v[220:223], v[4:7]
	s_setprio 0
	s_add_i32 s66, s66, 2
	s_add_u32 s42, s42, 0x100
	s_addc_u32 s43, s43, 0
	s_add_u32 s64, s64, 0x100
	s_addc_u32 s65, s65, 0
	s_cmp_gt_u32 s66, 29
	s_cbranch_scc0 .LBB0_225

; #define PG8_STAGE(bufoff, gbase, voff) do { _Pragma("unroll") for (int _i = 0; _i < 2; ++_i) \
;     __builtin_amdgcn_global_load_lds((const unsigned*)((const char*)(gbase) + (voff)[_i]), (LAS unsigned*)(lds + (bufoff) + ldsw + _i * 8192), 16, 0, 0); } while (0)
; #define PG8_LDA(dst, b, h) do { _Pragma("unroll") for (int m = 0; m < 4; ++m) _Pragma("unroll") for (int k = 0; k < 2; ++k) dst[m][k] = *(const LAS bf16x8*)(lds + PG8_SA(b, h) + aoff + m * 2048 + k * 1024); } while (0)
; #define PG8_LDB(dst, b, h) do { _Pragma("unroll") for (int n = 0; n < 2; ++n) _Pragma("unroll") for (int k = 0; k < 2; ++k) dst[n][k] = *(const LAS bf16x8*)(lds + PG8_SB(b, h) + boff + n * 2048 + k * 1024); } while (0)
; #define PG8_MMA(ai, bj, At, Bt) do { __builtin_amdgcn_s_setprio(1); _Pragma("unroll") for (int m = 0; m < 4; ++m) _Pragma("unroll") for (int n = 0; n < 2; ++n) _Pragma("unroll") for (int k = 0; k < 2; ++k) \
;     acc[ai][bj][m][n] = __builtin_amdgcn_mfma_f32_16x16x32_bf16(Bt[n][k], At[m][k], acc[ai][bj][m][n], 0, 0, 0); __builtin_amdgcn_s_setprio(0); } while (0)
; #define PG8_WAIT_L(n) asm volatile("s_waitcnt lgkmcnt(" #n ")" ::: "memory")
; #define PG8_BAR __builtin_amdgcn_s_barrier()
; #define PG8_SCHED __builtin_amdgcn_sched_barrier(0)
; template <class Epi>
; DI void gemm_phase(LAS unsigned char* lds, const Gemm g, const Epi& E) {
;     ...
;     const bool has_next = S.next(ui + 1, nxt);
;     const char* nA = has_next ? PG8_APTR(nxt) : cA; const char* nB = has_next ? (const char*)g.Bt + (size_t)nxt.pn * tstepB : cB;
;     for (int t = 0; t < nt; t += 2) {
;       const bool last = (t == nt - 2);
;       const char* a1 = cA + (size_t)(t + 1) * kstep;
;       const char* a2 = last ? nA : cA + (size_t)(t + 2) * kstep; const char* b2 = last ? nB : cB + (size_t)(t + 2) * kstep;
;       const char* a3 = a2 + kstep; const char* b3 = b2 + kstep;
;       PG8_LDB(B0, 0, 0); PG8_SCHED; PG8_LDA(At, 0, 0); PG8_STAGE(PG8_SA(1, 1), a1 + hstepA, voffA);
;       PG8_WAIT_L(8); PG8_BAR; PG8_WAIT_L(0); PG8_MMA(0, 0, At, B0); PG8_BAR; PG8_SCHED;
;       PG8_LDB(B1, 0, 1); PG8_STAGE(PG8_SB(0, 0), b2, voffB);
;       PG8_BAR; PG8_WAIT_L(0); PG8_MMA(0, 1, At, B1); PG8_BAR;
;       PG8_LDA(At, 0, 1); PG8_STAGE(PG8_SA(0, 0), a2, voffA);
;       PG8_BAR; PG8_WAIT_L(0); PG8_MMA(1, 0, At, B0); PG8_BAR; PG8_SCHED;
.LBB0_513:
	s_add_u32 s42, s58, 0x80
	s_addc_u32 s43, s59, 0
	s_add_u32 s58, s56, 0x100
	s_addc_u32 s59, s57, 0
	s_mov_b32 s44, 0
	v_add_u32_e32 v248, 0x10000, v193
	ds_read_b128 v[132:135], v248
	ds_read_b128 v[136:139], v248 offset:1024
	ds_read_b128 v[140:143], v248 offset:2048
	ds_read_b128 v[144:147], v248 offset:3072
	s_add_i32 m0, s64, 0xc000
	ds_read_b128 v[148:151], v195
	ds_read_b128 v[152:155], v195 offset:1024
	ds_read_b128 v[156:159], v195 offset:2048
	ds_read_b128 v[160:163], v195 offset:3072
	ds_read_b128 v[196:199], v195 offset:4096
	ds_read_b128 v[200:203], v195 offset:5120
	ds_read_b128 v[208:211], v195 offset:6144
	ds_read_b128 v[212:215], v195 offset:7168
	global_load_lds_dwordx4 v186, s[42:43]
	s_add_i32 m0, s64, 0xe000
	s_nop 0
	global_load_lds_dwordx4 v188, s[42:43]
	s_waitcnt lgkmcnt(8)
	s_barrier
	s_setprio 1
	s_waitcnt lgkmcnt(0)
	v_mfma_f32_16x16x32_bf16 v[128:131], v[132:135], v[148:151], 0
	s_add_i32 s78, s44, 2
	v_mfma_f32_16x16x32_bf16 v[124:127], v[140:143], v[148:151], 0
	s_add_u32 s56, s42, 0x80
	s_addc_u32 s45, s43, 0
	v_mfma_f32_16x16x32_bf16 v[116:119], v[132:135], v[156:159], 0
	s_add_i32 s79, 0, 0x10000
	v_mfma_f32_16x16x32_bf16 v[108:111], v[140:143], v[156:159], 0
	s_cmp_eq_u32 s72, s44
	s_cselect_b32 s44, s52, s56
	s_cselect_b32 s45, s53, s45
	s_cselect_b32 s57, s55, s59
	s_cselect_b32 s56, s54, s58
	v_mfma_f32_16x16x32_bf16 v[100:103], v[132:135], v[196:199], 0
	v_mfma_f32_16x16x32_bf16 v[92:95], v[140:143], v[196:199], 0
	v_mfma_f32_16x16x32_bf16 v[84:87], v[132:135], v[208:211], 0
	v_mfma_f32_16x16x32_bf16 v[76:79], v[140:143], v[208:211], 0
	v_mfma_f32_16x16x32_bf16 v[128:131], v[136:139], v[152:155], v[128:131]
	v_mfma_f32_16x16x32_bf16 v[124:127], v[144:147], v[152:155], v[124:127]
	v_mfma_f32_16x16x32_bf16 v[116:119], v[136:139], v[160:163], v[116:119]
	v_mfma_f32_16x16x32_bf16 v[108:111], v[144:147], v[160:163], v[108:111]
	v_mfma_f32_16x16x32_bf16 v[100:103], v[136:139], v[200:203], v[100:103]
	v_mfma_f32_16x16x32_bf16 v[92:95], v[144:147], v[200:203], v[92:95]
	s_setprio 2
	s_barrier
	v_mfma_f32_16x16x32_bf16 v[84:87], v[136:139], v[212:215], v[84:87]
	v_mfma_f32_16x16x32_bf16 v[76:79], v[144:147], v[212:215], v[76:79]
	s_setprio 0
	s_add_i32 s80, 0, 0x14000
	s_add_i32 s79, s79, s63
	ds_read_b128 v[216:219], v248 offset:16384
	ds_read_b128 v[220:223], v248 offset:17408
	ds_read_b128 v[224:227], v248 offset:18432
	ds_read_b128 v[228:231], v248 offset:19456
	s_add_u32 s98, s56, 0x80
	s_addc_u32 s99, s57, 0
	s_mov_b32 m0, s79
	global_load_lds_dwordx4 v2, s[56:57]
	s_add_i32 m0, s79, 0x2000
	s_nop 0
	global_load_lds_dwordx4 v184, s[56:57]
	s_barrier
	s_setprio 1
	s_waitcnt lgkmcnt(0)
	v_mfma_f32_16x16x32_bf16 v[120:123], v[216:219], v[148:151], 0
	v_mfma_f32_16x16x32_bf16 v[112:115], v[224:227], v[148:151], 0
	v_mfma_f32_16x16x32_bf16 v[104:107], v[216:219], v[156:159], 0
	v_mfma_f32_16x16x32_bf16 v[96:99], v[224:227], v[156:159], 0
	v_mfma_f32_16x16x32_bf16 v[88:91], v[216:219], v[196:199], 0
	v_mfma_f32_16x16x32_bf16 v[80:83], v[224:227], v[196:199], 0
	v_mfma_f32_16x16x32_bf16 v[72:75], v[216:219], v[208:211], 0
	v_mfma_f32_16x16x32_bf16 v[68:71], v[224:227], v[208:211], 0
	v_mfma_f32_16x16x32_bf16 v[120:123], v[220:223], v[152:155], v[120:123]
	v_mfma_f32_16x16x32_bf16 v[112:115], v[228:231], v[152:155], v[112:115]
	v_mfma_f32_16x16x32_bf16 v[104:107], v[220:223], v[160:163], v[104:107]
	v_mfma_f32_16x16x32_bf16 v[96:99], v[228:231], v[160:163], v[96:99]
	v_mfma_f32_16x16x32_bf16 v[88:91], v[220:223], v[200:203], v[88:91]
	v_mfma_f32_16x16x32_bf16 v[80:83], v[228:231], v[200:203], v[80:83]
	s_setprio 2
	s_barrier
	v_mfma_f32_16x16x32_bf16 v[72:75], v[220:223], v[212:215], v[72:75]
	v_mfma_f32_16x16x32_bf16 v[68:71], v[228:231], v[212:215], v[68:71]
	s_setprio 0
	s_mov_b32 m0, s64
	s_add_u32 s100, s44, 0x80
	s_addc_u32 s101, s45, 0
	ds_read_b128 v[148:151], v195 offset:16384
	ds_read_b128 v[152:155], v195 offset:17408
	ds_read_b128 v[156:159], v195 offset:18432
	ds_read_b128 v[160:163], v195 offset:19456
	ds_read_b128 v[196:199], v195 offset:20480
	ds_read_b128 v[200:203], v195 offset:21504
	ds_read_b128 v[208:211], v195 offset:22528
	ds_read_b128 v[212:215], v195 offset:23552
	global_load_lds_dwordx4 v180, s[44:45]
	s_mov_b32 m0, s65
	s_nop 0
	global_load_lds_dwordx4 v182, s[44:45]
	s_waitcnt vmcnt(10)
	s_barrier
	s_setprio 1
	s_waitcnt lgkmcnt(0)
	v_mfma_f32_16x16x32_bf16 v[64:67], v[132:135], v[148:151], 0
	v_mfma_f32_16x16x32_bf16 v[60:63], v[140:143], v[148:151], 0
	v_mfma_f32_16x16x32_bf16 v[56:59], v[132:135], v[156:159], 0
	v_mfma_f32_16x16x32_bf16 v[48:51], v[140:143], v[156:159], 0
	v_mfma_f32_16x16x32_bf16 v[40:43], v[132:135], v[196:199], 0
	v_mfma_f32_16x16x32_bf16 v[32:35], v[140:143], v[196:199], 0
	v_mfma_f32_16x16x32_bf16 v[24:27], v[132:135], v[208:211], 0
	v_mfma_f32_16x16x32_bf16 v[16:19], v[140:143], v[208:211], 0
	v_mfma_f32_16x16x32_bf16 v[64:67], v[136:139], v[152:155], v[64:67]
	v_mfma_f32_16x16x32_bf16 v[60:63], v[144:147], v[152:155], v[60:63]
	v_mfma_f32_16x16x32_bf16 v[56:59], v[136:139], v[160:163], v[56:59]
	v_mfma_f32_16x16x32_bf16 v[48:51], v[144:147], v[160:163], v[48:51]
	v_mfma_f32_16x16x32_bf16 v[40:43], v[136:139], v[200:203], v[40:43]
	v_mfma_f32_16x16x32_bf16 v[32:35], v[144:147], v[200:203], v[32:35]
	s_setprio 2
	s_barrier
; #define PG8_STAGE(bufoff, gbase, voff) do { _Pragma("unroll") for (int _i = 0; _i < 2; ++_i) \
;     __builtin_amdgcn_global_load_lds((const unsigned*)((const char*)(gbase) + (voff)[_i]), (LAS unsigned*)(lds + (bufoff) + ldsw + _i * 8192), 16, 0, 0); } while (0)
; #define PG8_LDA(dst, b, h) do { _Pragma("unroll") for (int m = 0; m < 4; ++m) _Pragma("unroll") for (int k = 0; k < 2; ++k) dst[m][k] = *(const LAS bf16x8*)(lds + PG8_SA(b, h) + aoff + m * 2048 + k * 1024); } while (0)
; #define PG8_LDB(dst, b, h) do { _Pragma("unroll") for (int n = 0; n < 2; ++n) _Pragma("unroll") for (int k = 0; k < 2; ++k) dst[n][k] = *(const LAS bf16x8*)(lds + PG8_SB(b, h) + boff + n * 2048 + k * 1024); } while (0)
; #define PG8_MMA(ai, bj, At, Bt) do { __builtin_amdgcn_s_setprio(1); _Pragma("unroll") for (int m = 0; m < 4; ++m) _Pragma("unroll") for (int n = 0; n < 2; ++n) _Pragma("unroll") for (int k = 0; k < 2; ++k) \
;     acc[ai][bj][m][n] = __builtin_amdgcn_mfma_f32_16x16x32_bf16(Bt[n][k], At[m][k], acc[ai][bj][m][n], 0, 0, 0); __builtin_amdgcn_s_setprio(0); } while (0)
; #define PG8_WAIT_V(n) asm volatile("s_waitcnt vmcnt(" #n ")" ::: "memory")
; #define PG8_WAIT_L(n) asm volatile("s_waitcnt lgkmcnt(" #n ")" ::: "memory")
; #define PG8_BAR __builtin_amdgcn_s_barrier()
; #define PG8_SCHED __builtin_amdgcn_sched_barrier(0)
; template <class Epi>
; DI void gemm_phase(LAS unsigned char* lds, const Gemm g, const Epi& E) {
;     ...
;       PG8_STAGE(PG8_SB(0, 1), b2 + hstepB, voffB);
;       PG8_WAIT_V(6); PG8_BAR; PG8_MMA(1, 1, At, B1); PG8_BAR;
;       PG8_LDB(B0, 1, 0); PG8_SCHED; PG8_LDA(At, 1, 0); PG8_STAGE(PG8_SA(0, 1), a2 + hstepA, voffA);
;       PG8_WAIT_L(8); PG8_BAR; PG8_WAIT_L(0); PG8_MMA(0, 0, At, B0); PG8_BAR; PG8_SCHED;
;       PG8_LDB(B1, 1, 1); PG8_STAGE(PG8_SB(1, 0), b3, voffB);
;       PG8_BAR; PG8_WAIT_L(0); PG8_MMA(0, 1, At, B1); PG8_BAR;
;       PG8_LDA(At, 1, 1); PG8_STAGE(PG8_SA(1, 0), a3, voffA);
;       PG8_BAR; PG8_WAIT_L(0); PG8_MMA(1, 0, At, B0); PG8_BAR; PG8_SCHED;
	v_mfma_f32_16x16x32_bf16 v[24:27], v[136:139], v[212:215], v[24:27]
	v_mfma_f32_16x16x32_bf16 v[16:19], v[144:147], v[212:215], v[16:19]
	s_setprio 0
	ds_read_b128 v[132:135], v248 offset:32768
	ds_read_b128 v[136:139], v248 offset:33792
	ds_read_b128 v[140:143], v248 offset:34816
	ds_read_b128 v[144:147], v248 offset:35840
	s_add_u32 s56, s56, s18
	s_addc_u32 s57, s57, s19
	s_add_i32 s79, s80, s63
	v_lshl_add_u64 v[238:239], s[56:57], 0, v[2:3]
	s_mov_b32 m0, s79
	v_lshl_add_u64 v[240:241], s[56:57], 0, v[184:185]
	global_load_lds_dwordx4 v[238:239], off
	s_add_i32 m0, s79, 0x2000
	s_nop 0
	global_load_lds_dwordx4 v[240:241], off
	s_waitcnt vmcnt(6)
	s_barrier
	s_setprio 1
	v_mfma_f32_16x16x32_bf16 v[52:55], v[216:219], v[148:151], 0
	v_mfma_f32_16x16x32_bf16 v[44:47], v[224:227], v[148:151], 0
	v_mfma_f32_16x16x32_bf16 v[36:39], v[216:219], v[156:159], 0
	v_mfma_f32_16x16x32_bf16 v[28:31], v[224:227], v[156:159], 0
	v_mfma_f32_16x16x32_bf16 v[20:23], v[216:219], v[196:199], 0
	v_mfma_f32_16x16x32_bf16 v[12:15], v[224:227], v[196:199], 0
	v_mfma_f32_16x16x32_bf16 v[8:11], v[216:219], v[208:211], 0
	v_mfma_f32_16x16x32_bf16 v[4:7], v[224:227], v[208:211], 0
	v_mfma_f32_16x16x32_bf16 v[52:55], v[220:223], v[152:155], v[52:55]
	v_mfma_f32_16x16x32_bf16 v[44:47], v[228:231], v[152:155], v[44:47]
	v_mfma_f32_16x16x32_bf16 v[36:39], v[220:223], v[160:163], v[36:39]
	v_mfma_f32_16x16x32_bf16 v[28:31], v[228:231], v[160:163], v[28:31]
	v_mfma_f32_16x16x32_bf16 v[20:23], v[220:223], v[200:203], v[20:23]
	v_mfma_f32_16x16x32_bf16 v[12:15], v[228:231], v[200:203], v[12:15]
	s_setprio 2
	s_barrier
	v_mfma_f32_16x16x32_bf16 v[8:11], v[220:223], v[212:215], v[8:11]
	v_mfma_f32_16x16x32_bf16 v[4:7], v[228:231], v[212:215], v[4:7]
	s_setprio 0
	s_add_i32 s56, 0, 0x18000
	s_add_u32 s44, s44, s8
	s_addc_u32 s45, s45, 0
	s_mov_b32 m0, s66
	ds_read_b128 v[148:151], v195 offset:32768
	ds_read_b128 v[152:155], v195 offset:33792
	ds_read_b128 v[156:159], v195 offset:34816
	ds_read_b128 v[160:163], v195 offset:35840
	ds_read_b128 v[196:199], v195 offset:36864
	ds_read_b128 v[200:203], v195 offset:37888
	ds_read_b128 v[208:211], v195 offset:38912
	ds_read_b128 v[212:215], v195 offset:39936
	global_load_lds_dwordx4 v180, s[44:45]
	s_mov_b32 m0, s67
	s_nop 0
	global_load_lds_dwordx4 v182, s[44:45]
	s_waitcnt lgkmcnt(8)
	s_barrier
	s_setprio 1
	s_waitcnt lgkmcnt(0)
	v_mfma_f32_16x16x32_bf16 v[128:131], v[132:135], v[148:151], v[128:131]
	v_mfma_f32_16x16x32_bf16 v[124:127], v[140:143], v[148:151], v[124:127]
	v_mfma_f32_16x16x32_bf16 v[116:119], v[132:135], v[156:159], v[116:119]
	v_mfma_f32_16x16x32_bf16 v[108:111], v[140:143], v[156:159], v[108:111]
	v_mfma_f32_16x16x32_bf16 v[100:103], v[132:135], v[196:199], v[100:103]
	v_mfma_f32_16x16x32_bf16 v[92:95], v[140:143], v[196:199], v[92:95]
	v_mfma_f32_16x16x32_bf16 v[84:87], v[132:135], v[208:211], v[84:87]
	v_mfma_f32_16x16x32_bf16 v[76:79], v[140:143], v[208:211], v[76:79]
	v_mfma_f32_16x16x32_bf16 v[128:131], v[136:139], v[152:155], v[128:131]
	v_mfma_f32_16x16x32_bf16 v[124:127], v[144:147], v[152:155], v[124:127]
	v_mfma_f32_16x16x32_bf16 v[116:119], v[136:139], v[160:163], v[116:119]
	v_mfma_f32_16x16x32_bf16 v[108:111], v[144:147], v[160:163], v[108:111]
	v_mfma_f32_16x16x32_bf16 v[100:103], v[136:139], v[200:203], v[100:103]
	v_mfma_f32_16x16x32_bf16 v[92:95], v[144:147], v[200:203], v[92:95]
	s_setprio 2
	s_barrier
	v_mfma_f32_16x16x32_bf16 v[84:87], v[136:139], v[212:215], v[84:87]
	v_mfma_f32_16x16x32_bf16 v[76:79], v[144:147], v[212:215], v[76:79]
	s_setprio 0
	s_add_i32 s44, 0, 0x1c000
	s_add_i32 s45, s56, s63
	s_mov_b32 m0, s45
	ds_read_b128 v[216:219], v248 offset:49152
	ds_read_b128 v[220:223], v248 offset:50176
	ds_read_b128 v[224:227], v248 offset:51200
	ds_read_b128 v[228:231], v248 offset:52224
	global_load_lds_dwordx4 v2, s[98:99]
	s_add_i32 m0, s45, 0x2000
	s_nop 0
	global_load_lds_dwordx4 v184, s[98:99]
	s_barrier
	s_setprio 1
	s_waitcnt lgkmcnt(0)
	v_mfma_f32_16x16x32_bf16 v[120:123], v[216:219], v[148:151], v[120:123]
	v_mfma_f32_16x16x32_bf16 v[112:115], v[224:227], v[148:151], v[112:115]
	v_mfma_f32_16x16x32_bf16 v[104:107], v[216:219], v[156:159], v[104:107]
	v_mfma_f32_16x16x32_bf16 v[96:99], v[224:227], v[156:159], v[96:99]
	v_mfma_f32_16x16x32_bf16 v[88:91], v[216:219], v[196:199], v[88:91]
	v_mfma_f32_16x16x32_bf16 v[80:83], v[224:227], v[196:199], v[80:83]
	v_mfma_f32_16x16x32_bf16 v[72:75], v[216:219], v[208:211], v[72:75]
	v_mfma_f32_16x16x32_bf16 v[68:71], v[224:227], v[208:211], v[68:71]
	v_mfma_f32_16x16x32_bf16 v[120:123], v[220:223], v[152:155], v[120:123]
	v_mfma_f32_16x16x32_bf16 v[112:115], v[228:231], v[152:155], v[112:115]
	v_mfma_f32_16x16x32_bf16 v[104:107], v[220:223], v[160:163], v[104:107]
	v_mfma_f32_16x16x32_bf16 v[96:99], v[228:231], v[160:163], v[96:99]
	v_mfma_f32_16x16x32_bf16 v[88:91], v[220:223], v[200:203], v[88:91]
	v_mfma_f32_16x16x32_bf16 v[80:83], v[228:231], v[200:203], v[80:83]
	s_setprio 2
	s_barrier
	v_mfma_f32_16x16x32_bf16 v[72:75], v[220:223], v[212:215], v[72:75]
	v_mfma_f32_16x16x32_bf16 v[68:71], v[228:231], v[212:215], v[68:71]
	s_setprio 0
	s_mov_b32 m0, s69
	ds_read_b128 v[148:151], v195 offset:49152
	ds_read_b128 v[152:155], v195 offset:50176
	ds_read_b128 v[156:159], v195 offset:51200
	ds_read_b128 v[160:163], v195 offset:52224
	ds_read_b128 v[196:199], v195 offset:53248
	ds_read_b128 v[200:203], v195 offset:54272
	ds_read_b128 v[208:211], v195 offset:55296
	ds_read_b128 v[212:215], v195 offset:56320
	global_load_lds_dwordx4 v180, s[100:101]
	s_mov_b32 m0, s71
	s_nop 0
	global_load_lds_dwordx4 v182, s[100:101]
	s_waitcnt vmcnt(10)
	s_barrier
; #define PG8_STAGE(bufoff, gbase, voff) do { _Pragma("unroll") for (int _i = 0; _i < 2; ++_i) \
;     __builtin_amdgcn_global_load_lds((const unsigned*)((const char*)(gbase) + (voff)[_i]), (LAS unsigned*)(lds + (bufoff) + ldsw + _i * 8192), 16, 0, 0); } while (0)
; #define PG8_LDA(dst, b, h) do { _Pragma("unroll") for (int m = 0; m < 4; ++m) _Pragma("unroll") for (int k = 0; k < 2; ++k) dst[m][k] = *(const LAS bf16x8*)(lds + PG8_SA(b, h) + aoff + m * 2048 + k * 1024); } while (0)
; #define PG8_LDB(dst, b, h) do { _Pragma("unroll") for (int n = 0; n < 2; ++n) _Pragma("unroll") for (int k = 0; k < 2; ++k) dst[n][k] = *(const LAS bf16x8*)(lds + PG8_SB(b, h) + boff + n * 2048 + k * 1024); } while (0)
; #define PG8_MMA(ai, bj, At, Bt) do { __builtin_amdgcn_s_setprio(1); _Pragma("unroll") for (int m = 0; m < 4; ++m) _Pragma("unroll") for (int n = 0; n < 2; ++n) _Pragma("unroll") for (int k = 0; k < 2; ++k) \
;     acc[ai][bj][m][n] = __builtin_amdgcn_mfma_f32_16x16x32_bf16(Bt[n][k], At[m][k], acc[ai][bj][m][n], 0, 0, 0); __builtin_amdgcn_s_setprio(0); } while (0)
; #define PG8_WAIT_V(n) asm volatile("s_waitcnt vmcnt(" #n ")" ::: "memory")
; #define PG8_WAIT_L(n) asm volatile("s_waitcnt lgkmcnt(" #n ")" ::: "memory")
; #define PG8_BAR __builtin_amdgcn_s_barrier()
; #define PG8_SCHED __builtin_amdgcn_sched_barrier(0)
; template <class Epi>
; DI void gemm_phase(LAS unsigned char* lds, const Gemm g, const Epi& E) {
;     ...
;       PG8_LDB(B0, 0, 0); PG8_SCHED; PG8_LDA(At, 0, 0); PG8_STAGE(PG8_SA(1, 1), a1 + hstepA, voffA);
;       PG8_WAIT_L(8); PG8_BAR; PG8_WAIT_L(0); PG8_MMA(0, 0, At, B0); PG8_BAR; PG8_SCHED;
;       PG8_LDB(B1, 0, 1); PG8_STAGE(PG8_SB(0, 0), b2, voffB);
;       PG8_BAR; PG8_WAIT_L(0); PG8_MMA(0, 1, At, B1); PG8_BAR;
;     ...
;       PG8_BAR; PG8_WAIT_L(0); PG8_MMA(1, 0, At, B0); PG8_BAR; PG8_SCHED;
;       PG8_STAGE(PG8_SB(1, 1), b3 + hstepB, voffB);
;       PG8_WAIT_V(6); PG8_BAR; PG8_MMA(1, 1, At, B1); PG8_BAR;
	s_setprio 1
	s_waitcnt lgkmcnt(0)
	v_mfma_f32_16x16x32_bf16 v[64:67], v[132:135], v[148:151], v[64:67]
	v_mfma_f32_16x16x32_bf16 v[60:63], v[140:143], v[148:151], v[60:63]
	v_mfma_f32_16x16x32_bf16 v[56:59], v[132:135], v[156:159], v[56:59]
	v_mfma_f32_16x16x32_bf16 v[48:51], v[140:143], v[156:159], v[48:51]
	v_mfma_f32_16x16x32_bf16 v[40:43], v[132:135], v[196:199], v[40:43]
	v_mfma_f32_16x16x32_bf16 v[32:35], v[140:143], v[196:199], v[32:35]
	v_mfma_f32_16x16x32_bf16 v[24:27], v[132:135], v[208:211], v[24:27]
	v_mfma_f32_16x16x32_bf16 v[16:19], v[140:143], v[208:211], v[16:19]
	v_mfma_f32_16x16x32_bf16 v[64:67], v[136:139], v[152:155], v[64:67]
	v_mfma_f32_16x16x32_bf16 v[60:63], v[144:147], v[152:155], v[60:63]
	v_mfma_f32_16x16x32_bf16 v[56:59], v[136:139], v[160:163], v[56:59]
	v_mfma_f32_16x16x32_bf16 v[48:51], v[144:147], v[160:163], v[48:51]
	v_mfma_f32_16x16x32_bf16 v[40:43], v[136:139], v[200:203], v[40:43]
	v_mfma_f32_16x16x32_bf16 v[32:35], v[144:147], v[200:203], v[32:35]
	s_setprio 2
	s_barrier
	v_mfma_f32_16x16x32_bf16 v[24:27], v[136:139], v[212:215], v[24:27]
	v_mfma_f32_16x16x32_bf16 v[16:19], v[144:147], v[212:215], v[16:19]
	s_setprio 0
	ds_read_b128 v[132:135], v248
	ds_read_b128 v[136:139], v248 offset:1024
	ds_read_b128 v[140:143], v248 offset:2048
	ds_read_b128 v[144:147], v248 offset:3072
	s_add_i32 s44, s44, s63
	v_lshl_add_u64 v[246:247], v[238:239], 0, s[84:85]
	s_mov_b32 m0, s44
	s_nop 0
	global_load_lds_dwordx4 v[246:247], off
	v_lshl_add_u64 v[246:247], v[240:241], 0, s[84:85]
	s_add_i32 m0, s44, 0x2000
	s_nop 0
	global_load_lds_dwordx4 v[246:247], off
	s_waitcnt vmcnt(6)
	s_barrier
	s_setprio 1
	v_mfma_f32_16x16x32_bf16 v[52:55], v[216:219], v[148:151], v[52:55]
	v_mfma_f32_16x16x32_bf16 v[44:47], v[224:227], v[148:151], v[44:47]
	v_mfma_f32_16x16x32_bf16 v[36:39], v[216:219], v[156:159], v[36:39]
	v_mfma_f32_16x16x32_bf16 v[28:31], v[224:227], v[156:159], v[28:31]
	v_mfma_f32_16x16x32_bf16 v[20:23], v[216:219], v[196:199], v[20:23]
	v_mfma_f32_16x16x32_bf16 v[12:15], v[224:227], v[196:199], v[12:15]
	v_mfma_f32_16x16x32_bf16 v[8:11], v[216:219], v[208:211], v[8:11]
	v_mfma_f32_16x16x32_bf16 v[4:7], v[224:227], v[208:211], v[4:7]
	v_mfma_f32_16x16x32_bf16 v[52:55], v[220:223], v[152:155], v[52:55]
	v_mfma_f32_16x16x32_bf16 v[44:47], v[228:231], v[152:155], v[44:47]
	v_mfma_f32_16x16x32_bf16 v[36:39], v[220:223], v[160:163], v[36:39]
	v_mfma_f32_16x16x32_bf16 v[28:31], v[228:231], v[160:163], v[28:31]
	v_mfma_f32_16x16x32_bf16 v[20:23], v[220:223], v[200:203], v[20:23]
	v_mfma_f32_16x16x32_bf16 v[12:15], v[228:231], v[200:203], v[12:15]
	s_setprio 2
	s_barrier
	v_mfma_f32_16x16x32_bf16 v[8:11], v[220:223], v[212:215], v[8:11]
	v_mfma_f32_16x16x32_bf16 v[4:7], v[228:231], v[212:215], v[4:7]
	s_setprio 0
	s_add_u32 s42, s42, 0x100
	s_addc_u32 s43, s43, 0
	s_add_u32 s58, s58, 0x100
	s_addc_u32 s59, s59, 0
	s_cmp_ge_u32 s78, s68
	s_mov_b32 s44, s78
	s_cbranch_scc1 .Lpeel_exit_514
.LBB0_514:
	s_add_i32 m0, s64, 0xc000
	ds_read_b128 v[148:151], v195
	ds_read_b128 v[152:155], v195 offset:1024
	ds_read_b128 v[156:159], v195 offset:2048
	ds_read_b128 v[160:163], v195 offset:3072
	ds_read_b128 v[196:199], v195 offset:4096
	ds_read_b128 v[200:203], v195 offset:5120
	ds_read_b128 v[208:211], v195 offset:6144
	ds_read_b128 v[212:215], v195 offset:7168
	global_load_lds_dwordx4 v186, s[42:43]
	s_add_i32 m0, s64, 0xe000
	s_nop 0
	global_load_lds_dwordx4 v188, s[42:43]
	s_waitcnt lgkmcnt(8)
	s_barrier
	s_setprio 1
	s_waitcnt lgkmcnt(0)
	v_mfma_f32_16x16x32_bf16 v[128:131], v[132:135], v[148:151], v[128:131]
	s_add_i32 s78, s44, 2
	v_mfma_f32_16x16x32_bf16 v[124:127], v[140:143], v[148:151], v[124:127]
	s_add_u32 s56, s42, 0x80
	s_addc_u32 s45, s43, 0
	v_mfma_f32_16x16x32_bf16 v[116:119], v[132:135], v[156:159], v[116:119]
	s_add_i32 s79, 0, 0x10000
	v_mfma_f32_16x16x32_bf16 v[108:111], v[140:143], v[156:159], v[108:111]
	s_cmp_eq_u32 s72, s44
	s_cselect_b32 s44, s52, s56
	s_cselect_b32 s45, s53, s45
	s_cselect_b32 s57, s55, s59
	s_cselect_b32 s56, s54, s58
	v_mfma_f32_16x16x32_bf16 v[100:103], v[132:135], v[196:199], v[100:103]
	v_mfma_f32_16x16x32_bf16 v[92:95], v[140:143], v[196:199], v[92:95]
	v_mfma_f32_16x16x32_bf16 v[84:87], v[132:135], v[208:211], v[84:87]
	v_mfma_f32_16x16x32_bf16 v[76:79], v[140:143], v[208:211], v[76:79]
	v_mfma_f32_16x16x32_bf16 v[128:131], v[136:139], v[152:155], v[128:131]
	v_mfma_f32_16x16x32_bf16 v[124:127], v[144:147], v[152:155], v[124:127]
	v_mfma_f32_16x16x32_bf16 v[116:119], v[136:139], v[160:163], v[116:119]
	v_mfma_f32_16x16x32_bf16 v[108:111], v[144:147], v[160:163], v[108:111]
	v_mfma_f32_16x16x32_bf16 v[100:103], v[136:139], v[200:203], v[100:103]
	v_mfma_f32_16x16x32_bf16 v[92:95], v[144:147], v[200:203], v[92:95]
	s_setprio 2
	s_barrier
	v_mfma_f32_16x16x32_bf16 v[84:87], v[136:139], v[212:215], v[84:87]
	v_mfma_f32_16x16x32_bf16 v[76:79], v[144:147], v[212:215], v[76:79]
	s_setprio 0
	s_add_i32 s80, 0, 0x14000
	s_add_i32 s79, s79, s63
	ds_read_b128 v[216:219], v248 offset:16384
	ds_read_b128 v[220:223], v248 offset:17408
	ds_read_b128 v[224:227], v248 offset:18432
	ds_read_b128 v[228:231], v248 offset:19456
	s_add_u32 s98, s56, 0x80
	s_addc_u32 s99, s57, 0
	s_mov_b32 m0, s79
	global_load_lds_dwordx4 v2, s[56:57]
	s_add_i32 m0, s79, 0x2000
	s_nop 0
	global_load_lds_dwordx4 v184, s[56:57]
	s_barrier
; #define PG8_STAGE(bufoff, gbase, voff) do { _Pragma("unroll") for (int _i = 0; _i < 2; ++_i) \
;     __builtin_amdgcn_global_load_lds((const unsigned*)((const char*)(gbase) + (voff)[_i]), (LAS unsigned*)(lds + (bufoff) + ldsw + _i * 8192), 16, 0, 0); } while (0)
; #define PG8_LDA(dst, b, h) do { _Pragma("unroll") for (int m = 0; m < 4; ++m) _Pragma("unroll") for (int k = 0; k < 2; ++k) dst[m][k] = *(const LAS bf16x8*)(lds + PG8_SA(b, h) + aoff + m * 2048 + k * 1024); } while (0)
; #define PG8_LDB(dst, b, h) do { _Pragma("unroll") for (int n = 0; n < 2; ++n) _Pragma("unroll") for (int k = 0; k < 2; ++k) dst[n][k] = *(const LAS bf16x8*)(lds + PG8_SB(b, h) + boff + n * 2048 + k * 1024); } while (0)
; #define PG8_MMA(ai, bj, At, Bt) do { __builtin_amdgcn_s_setprio(1); _Pragma("unroll") for (int m = 0; m < 4; ++m) _Pragma("unroll") for (int n = 0; n < 2; ++n) _Pragma("unroll") for (int k = 0; k < 2; ++k) \
;     acc[ai][bj][m][n] = __builtin_amdgcn_mfma_f32_16x16x32_bf16(Bt[n][k], At[m][k], acc[ai][bj][m][n], 0, 0, 0); __builtin_amdgcn_s_setprio(0); } while (0)
; #define PG8_WAIT_V(n) asm volatile("s_waitcnt vmcnt(" #n ")" ::: "memory")
; #define PG8_WAIT_L(n) asm volatile("s_waitcnt lgkmcnt(" #n ")" ::: "memory")
; #define PG8_BAR __builtin_amdgcn_s_barrier()
; #define PG8_SCHED __builtin_amdgcn_sched_barrier(0)
; template <class Epi>
; DI void gemm_phase(LAS unsigned char* lds, const Gemm g, const Epi& E) {
;     ...
;       PG8_BAR; PG8_WAIT_L(0); PG8_MMA(0, 1, At, B1); PG8_BAR;
;       PG8_LDA(At, 0, 1); PG8_STAGE(PG8_SA(0, 0), a2, voffA);
;       PG8_BAR; PG8_WAIT_L(0); PG8_MMA(1, 0, At, B0); PG8_BAR; PG8_SCHED;
;       PG8_STAGE(PG8_SB(0, 1), b2 + hstepB, voffB);
;       PG8_WAIT_V(6); PG8_BAR; PG8_MMA(1, 1, At, B1); PG8_BAR;
;       PG8_LDB(B0, 1, 0); PG8_SCHED; PG8_LDA(At, 1, 0); PG8_STAGE(PG8_SA(0, 1), a2 + hstepA, voffA);
;       PG8_WAIT_L(8); PG8_BAR; PG8_WAIT_L(0); PG8_MMA(0, 0, At, B0); PG8_BAR; PG8_SCHED;
;       PG8_LDB(B1, 1, 1); PG8_STAGE(PG8_SB(1, 0), b3, voffB);
;       PG8_BAR; PG8_WAIT_L(0); PG8_MMA(0, 1, At, B1); PG8_BAR;
;       PG8_LDA(At, 1, 1); PG8_STAGE(PG8_SA(1, 0), a3, voffA);
;       PG8_BAR; PG8_WAIT_L(0); PG8_MMA(1, 0, At, B0); PG8_BAR; PG8_SCHED;
	s_setprio 1
	s_waitcnt lgkmcnt(0)
	v_mfma_f32_16x16x32_bf16 v[120:123], v[216:219], v[148:151], v[120:123]
	v_mfma_f32_16x16x32_bf16 v[112:115], v[224:227], v[148:151], v[112:115]
	v_mfma_f32_16x16x32_bf16 v[104:107], v[216:219], v[156:159], v[104:107]
	v_mfma_f32_16x16x32_bf16 v[96:99], v[224:227], v[156:159], v[96:99]
	v_mfma_f32_16x16x32_bf16 v[88:91], v[216:219], v[196:199], v[88:91]
	v_mfma_f32_16x16x32_bf16 v[80:83], v[224:227], v[196:199], v[80:83]
	v_mfma_f32_16x16x32_bf16 v[72:75], v[216:219], v[208:211], v[72:75]
	v_mfma_f32_16x16x32_bf16 v[68:71], v[224:227], v[208:211], v[68:71]
	v_mfma_f32_16x16x32_bf16 v[120:123], v[220:223], v[152:155], v[120:123]
	v_mfma_f32_16x16x32_bf16 v[112:115], v[228:231], v[152:155], v[112:115]
	v_mfma_f32_16x16x32_bf16 v[104:107], v[220:223], v[160:163], v[104:107]
	v_mfma_f32_16x16x32_bf16 v[96:99], v[228:231], v[160:163], v[96:99]
	v_mfma_f32_16x16x32_bf16 v[88:91], v[220:223], v[200:203], v[88:91]
	v_mfma_f32_16x16x32_bf16 v[80:83], v[228:231], v[200:203], v[80:83]
	s_setprio 2
	s_barrier
	v_mfma_f32_16x16x32_bf16 v[72:75], v[220:223], v[212:215], v[72:75]
	v_mfma_f32_16x16x32_bf16 v[68:71], v[228:231], v[212:215], v[68:71]
	s_setprio 0
	s_mov_b32 m0, s64
	s_add_u32 s100, s44, 0x80
	s_addc_u32 s101, s45, 0
	ds_read_b128 v[148:151], v195 offset:16384
	ds_read_b128 v[152:155], v195 offset:17408
	ds_read_b128 v[156:159], v195 offset:18432
	ds_read_b128 v[160:163], v195 offset:19456
	ds_read_b128 v[196:199], v195 offset:20480
	ds_read_b128 v[200:203], v195 offset:21504
	ds_read_b128 v[208:211], v195 offset:22528
	ds_read_b128 v[212:215], v195 offset:23552
	global_load_lds_dwordx4 v180, s[44:45]
	s_mov_b32 m0, s65
	s_nop 0
	global_load_lds_dwordx4 v182, s[44:45]
	s_waitcnt vmcnt(10)
	s_barrier
	s_setprio 1
	s_waitcnt lgkmcnt(0)
	v_mfma_f32_16x16x32_bf16 v[64:67], v[132:135], v[148:151], v[64:67]
	v_mfma_f32_16x16x32_bf16 v[60:63], v[140:143], v[148:151], v[60:63]
	v_mfma_f32_16x16x32_bf16 v[56:59], v[132:135], v[156:159], v[56:59]
	v_mfma_f32_16x16x32_bf16 v[48:51], v[140:143], v[156:159], v[48:51]
	v_mfma_f32_16x16x32_bf16 v[40:43], v[132:135], v[196:199], v[40:43]
	v_mfma_f32_16x16x32_bf16 v[32:35], v[140:143], v[196:199], v[32:35]
	v_mfma_f32_16x16x32_bf16 v[24:27], v[132:135], v[208:211], v[24:27]
	v_mfma_f32_16x16x32_bf16 v[16:19], v[140:143], v[208:211], v[16:19]
	v_mfma_f32_16x16x32_bf16 v[64:67], v[136:139], v[152:155], v[64:67]
	v_mfma_f32_16x16x32_bf16 v[60:63], v[144:147], v[152:155], v[60:63]
	v_mfma_f32_16x16x32_bf16 v[56:59], v[136:139], v[160:163], v[56:59]
	v_mfma_f32_16x16x32_bf16 v[48:51], v[144:147], v[160:163], v[48:51]
	v_mfma_f32_16x16x32_bf16 v[40:43], v[136:139], v[200:203], v[40:43]
	v_mfma_f32_16x16x32_bf16 v[32:35], v[144:147], v[200:203], v[32:35]
	s_setprio 2
	s_barrier
	v_mfma_f32_16x16x32_bf16 v[24:27], v[136:139], v[212:215], v[24:27]
	v_mfma_f32_16x16x32_bf16 v[16:19], v[144:147], v[212:215], v[16:19]
	s_setprio 0
	ds_read_b128 v[132:135], v248 offset:32768
	ds_read_b128 v[136:139], v248 offset:33792
	ds_read_b128 v[140:143], v248 offset:34816
	ds_read_b128 v[144:147], v248 offset:35840
	s_add_u32 s56, s56, s18
	s_addc_u32 s57, s57, s19
	s_add_i32 s79, s80, s63
	v_lshl_add_u64 v[238:239], s[56:57], 0, v[2:3]
	s_mov_b32 m0, s79
	v_lshl_add_u64 v[240:241], s[56:57], 0, v[184:185]
	global_load_lds_dwordx4 v[238:239], off
	s_add_i32 m0, s79, 0x2000
	s_nop 0
	global_load_lds_dwordx4 v[240:241], off
	s_waitcnt vmcnt(6)
	s_barrier
	s_setprio 1
	v_mfma_f32_16x16x32_bf16 v[52:55], v[216:219], v[148:151], v[52:55]
	v_mfma_f32_16x16x32_bf16 v[44:47], v[224:227], v[148:151], v[44:47]
	v_mfma_f32_16x16x32_bf16 v[36:39], v[216:219], v[156:159], v[36:39]
	v_mfma_f32_16x16x32_bf16 v[28:31], v[224:227], v[156:159], v[28:31]
	v_mfma_f32_16x16x32_bf16 v[20:23], v[216:219], v[196:199], v[20:23]
	v_mfma_f32_16x16x32_bf16 v[12:15], v[224:227], v[196:199], v[12:15]
	v_mfma_f32_16x16x32_bf16 v[8:11], v[216:219], v[208:211], v[8:11]
	v_mfma_f32_16x16x32_bf16 v[4:7], v[224:227], v[208:211], v[4:7]
	v_mfma_f32_16x16x32_bf16 v[52:55], v[220:223], v[152:155], v[52:55]
	v_mfma_f32_16x16x32_bf16 v[44:47], v[228:231], v[152:155], v[44:47]
	v_mfma_f32_16x16x32_bf16 v[36:39], v[220:223], v[160:163], v[36:39]
	v_mfma_f32_16x16x32_bf16 v[28:31], v[228:231], v[160:163], v[28:31]
	v_mfma_f32_16x16x32_bf16 v[20:23], v[220:223], v[200:203], v[20:23]
	v_mfma_f32_16x16x32_bf16 v[12:15], v[228:231], v[200:203], v[12:15]
	s_setprio 2
	s_barrier
	v_mfma_f32_16x16x32_bf16 v[8:11], v[220:223], v[212:215], v[8:11]
	v_mfma_f32_16x16x32_bf16 v[4:7], v[228:231], v[212:215], v[4:7]
	s_setprio 0
	s_add_i32 s56, 0, 0x18000
	s_add_u32 s44, s44, s8
	s_addc_u32 s45, s45, 0
	s_mov_b32 m0, s66
	ds_read_b128 v[148:151], v195 offset:32768
	ds_read_b128 v[152:155], v195 offset:33792
	ds_read_b128 v[156:159], v195 offset:34816
	ds_read_b128 v[160:163], v195 offset:35840
	ds_read_b128 v[196:199], v195 offset:36864
	ds_read_b128 v[200:203], v195 offset:37888
	ds_read_b128 v[208:211], v195 offset:38912
	ds_read_b128 v[212:215], v195 offset:39936
	global_load_lds_dwordx4 v180, s[44:45]
	s_mov_b32 m0, s67
	s_nop 0
	global_load_lds_dwordx4 v182, s[44:45]
	s_waitcnt lgkmcnt(8)
	s_barrier
; #define PG8_STAGE(bufoff, gbase, voff) do { _Pragma("unroll") for (int _i = 0; _i < 2; ++_i) \
;     __builtin_amdgcn_global_load_lds((const unsigned*)((const char*)(gbase) + (voff)[_i]), (LAS unsigned*)(lds + (bufoff) + ldsw + _i * 8192), 16, 0, 0); } while (0)
; #define PG8_LDA(dst, b, h) do { _Pragma("unroll") for (int m = 0; m < 4; ++m) _Pragma("unroll") for (int k = 0; k < 2; ++k) dst[m][k] = *(const LAS bf16x8*)(lds + PG8_SA(b, h) + aoff + m * 2048 + k * 1024); } while (0)
; #define PG8_LDB(dst, b, h) do { _Pragma("unroll") for (int n = 0; n < 2; ++n) _Pragma("unroll") for (int k = 0; k < 2; ++k) dst[n][k] = *(const LAS bf16x8*)(lds + PG8_SB(b, h) + boff + n * 2048 + k * 1024); } while (0)
; #define PG8_MMA(ai, bj, At, Bt) do { __builtin_amdgcn_s_setprio(1); _Pragma("unroll") for (int m = 0; m < 4; ++m) _Pragma("unroll") for (int n = 0; n < 2; ++n) _Pragma("unroll") for (int k = 0; k < 2; ++k) \
;     acc[ai][bj][m][n] = __builtin_amdgcn_mfma_f32_16x16x32_bf16(Bt[n][k], At[m][k], acc[ai][bj][m][n], 0, 0, 0); __builtin_amdgcn_s_setprio(0); } while (0)
; #define PG8_WAIT_V(n) asm volatile("s_waitcnt vmcnt(" #n ")" ::: "memory")
; #define PG8_WAIT_L(n) asm volatile("s_waitcnt lgkmcnt(" #n ")" ::: "memory")
; #define PG8_BAR __builtin_amdgcn_s_barrier()
; #define PG8_SCHED __builtin_amdgcn_sched_barrier(0)
; template <class Epi>
; DI void gemm_phase(LAS unsigned char* lds, const Gemm g, const Epi& E) {
;     ...
;       PG8_WAIT_L(8); PG8_BAR; PG8_WAIT_L(0); PG8_MMA(0, 0, At, B0); PG8_BAR; PG8_SCHED;
;       PG8_LDB(B1, 1, 1); PG8_STAGE(PG8_SB(1, 0), b3, voffB);
;       PG8_BAR; PG8_WAIT_L(0); PG8_MMA(0, 1, At, B1); PG8_BAR;
;       PG8_LDA(At, 1, 1); PG8_STAGE(PG8_SA(1, 0), a3, voffA);
;       PG8_BAR; PG8_WAIT_L(0); PG8_MMA(1, 0, At, B0); PG8_BAR; PG8_SCHED;
;       PG8_STAGE(PG8_SB(1, 1), b3 + hstepB, voffB);
;       PG8_WAIT_V(6); PG8_BAR; PG8_MMA(1, 1, At, B1); PG8_BAR;
	s_setprio 1
	s_waitcnt lgkmcnt(0)
	v_mfma_f32_16x16x32_bf16 v[128:131], v[132:135], v[148:151], v[128:131]
	v_mfma_f32_16x16x32_bf16 v[124:127], v[140:143], v[148:151], v[124:127]
	v_mfma_f32_16x16x32_bf16 v[116:119], v[132:135], v[156:159], v[116:119]
	v_mfma_f32_16x16x32_bf16 v[108:111], v[140:143], v[156:159], v[108:111]
	v_mfma_f32_16x16x32_bf16 v[100:103], v[132:135], v[196:199], v[100:103]
	v_mfma_f32_16x16x32_bf16 v[92:95], v[140:143], v[196:199], v[92:95]
	v_mfma_f32_16x16x32_bf16 v[84:87], v[132:135], v[208:211], v[84:87]
	v_mfma_f32_16x16x32_bf16 v[76:79], v[140:143], v[208:211], v[76:79]
	v_mfma_f32_16x16x32_bf16 v[128:131], v[136:139], v[152:155], v[128:131]
	v_mfma_f32_16x16x32_bf16 v[124:127], v[144:147], v[152:155], v[124:127]
	v_mfma_f32_16x16x32_bf16 v[116:119], v[136:139], v[160:163], v[116:119]
	v_mfma_f32_16x16x32_bf16 v[108:111], v[144:147], v[160:163], v[108:111]
	v_mfma_f32_16x16x32_bf16 v[100:103], v[136:139], v[200:203], v[100:103]
	v_mfma_f32_16x16x32_bf16 v[92:95], v[144:147], v[200:203], v[92:95]
	s_setprio 2
	s_barrier
	v_mfma_f32_16x16x32_bf16 v[84:87], v[136:139], v[212:215], v[84:87]
	v_mfma_f32_16x16x32_bf16 v[76:79], v[144:147], v[212:215], v[76:79]
	s_setprio 0
	s_add_i32 s44, 0, 0x1c000
	s_add_i32 s45, s56, s63
	s_mov_b32 m0, s45
	ds_read_b128 v[216:219], v248 offset:49152
	ds_read_b128 v[220:223], v248 offset:50176
	ds_read_b128 v[224:227], v248 offset:51200
	ds_read_b128 v[228:231], v248 offset:52224
	global_load_lds_dwordx4 v2, s[98:99]
	s_add_i32 m0, s45, 0x2000
	s_nop 0
	global_load_lds_dwordx4 v184, s[98:99]
	s_barrier
	s_setprio 1
	s_waitcnt lgkmcnt(0)
	v_mfma_f32_16x16x32_bf16 v[120:123], v[216:219], v[148:151], v[120:123]
	v_mfma_f32_16x16x32_bf16 v[112:115], v[224:227], v[148:151], v[112:115]
	v_mfma_f32_16x16x32_bf16 v[104:107], v[216:219], v[156:159], v[104:107]
	v_mfma_f32_16x16x32_bf16 v[96:99], v[224:227], v[156:159], v[96:99]
	v_mfma_f32_16x16x32_bf16 v[88:91], v[216:219], v[196:199], v[88:91]
	v_mfma_f32_16x16x32_bf16 v[80:83], v[224:227], v[196:199], v[80:83]
	v_mfma_f32_16x16x32_bf16 v[72:75], v[216:219], v[208:211], v[72:75]
	v_mfma_f32_16x16x32_bf16 v[68:71], v[224:227], v[208:211], v[68:71]
	v_mfma_f32_16x16x32_bf16 v[120:123], v[220:223], v[152:155], v[120:123]
	v_mfma_f32_16x16x32_bf16 v[112:115], v[228:231], v[152:155], v[112:115]
	v_mfma_f32_16x16x32_bf16 v[104:107], v[220:223], v[160:163], v[104:107]
	v_mfma_f32_16x16x32_bf16 v[96:99], v[228:231], v[160:163], v[96:99]
	v_mfma_f32_16x16x32_bf16 v[88:91], v[220:223], v[200:203], v[88:91]
	v_mfma_f32_16x16x32_bf16 v[80:83], v[228:231], v[200:203], v[80:83]
	s_setprio 2
	s_barrier
	v_mfma_f32_16x16x32_bf16 v[72:75], v[220:223], v[212:215], v[72:75]
	v_mfma_f32_16x16x32_bf16 v[68:71], v[228:231], v[212:215], v[68:71]
	s_setprio 0
	s_mov_b32 m0, s69
	ds_read_b128 v[148:151], v195 offset:49152
	ds_read_b128 v[152:155], v195 offset:50176
	ds_read_b128 v[156:159], v195 offset:51200
	ds_read_b128 v[160:163], v195 offset:52224
	ds_read_b128 v[196:199], v195 offset:53248
	ds_read_b128 v[200:203], v195 offset:54272
	ds_read_b128 v[208:211], v195 offset:55296
	ds_read_b128 v[212:215], v195 offset:56320
	global_load_lds_dwordx4 v180, s[100:101]
	s_mov_b32 m0, s71
	s_nop 0
	global_load_lds_dwordx4 v182, s[100:101]
	s_waitcnt vmcnt(10)
	s_barrier
	s_setprio 1
	s_waitcnt lgkmcnt(0)
	v_mfma_f32_16x16x32_bf16 v[64:67], v[132:135], v[148:151], v[64:67]
	v_mfma_f32_16x16x32_bf16 v[60:63], v[140:143], v[148:151], v[60:63]
	v_mfma_f32_16x16x32_bf16 v[56:59], v[132:135], v[156:159], v[56:59]
	v_mfma_f32_16x16x32_bf16 v[48:51], v[140:143], v[156:159], v[48:51]
	v_mfma_f32_16x16x32_bf16 v[40:43], v[132:135], v[196:199], v[40:43]
	v_mfma_f32_16x16x32_bf16 v[32:35], v[140:143], v[196:199], v[32:35]
	v_mfma_f32_16x16x32_bf16 v[24:27], v[132:135], v[208:211], v[24:27]
	v_mfma_f32_16x16x32_bf16 v[16:19], v[140:143], v[208:211], v[16:19]
	v_mfma_f32_16x16x32_bf16 v[64:67], v[136:139], v[152:155], v[64:67]
	v_mfma_f32_16x16x32_bf16 v[60:63], v[144:147], v[152:155], v[60:63]
	v_mfma_f32_16x16x32_bf16 v[56:59], v[136:139], v[160:163], v[56:59]
	v_mfma_f32_16x16x32_bf16 v[48:51], v[144:147], v[160:163], v[48:51]
	v_mfma_f32_16x16x32_bf16 v[40:43], v[136:139], v[200:203], v[40:43]
	v_mfma_f32_16x16x32_bf16 v[32:35], v[144:147], v[200:203], v[32:35]
	s_setprio 2
	s_barrier
	v_mfma_f32_16x16x32_bf16 v[24:27], v[136:139], v[212:215], v[24:27]
	v_mfma_f32_16x16x32_bf16 v[16:19], v[144:147], v[212:215], v[16:19]
	s_setprio 0
	ds_read_b128 v[132:135], v248
	ds_read_b128 v[136:139], v248 offset:1024
	ds_read_b128 v[140:143], v248 offset:2048
	ds_read_b128 v[144:147], v248 offset:3072
	s_add_i32 s44, s44, s63
	v_lshl_add_u64 v[246:247], v[238:239], 0, s[84:85]
	s_mov_b32 m0, s44
	s_nop 0
	global_load_lds_dwordx4 v[246:247], off
	v_lshl_add_u64 v[246:247], v[240:241], 0, s[84:85]
	s_add_i32 m0, s44, 0x2000
	s_nop 0
	global_load_lds_dwordx4 v[246:247], off
	s_waitcnt vmcnt(6)
	s_barrier
	s_setprio 1
	v_mfma_f32_16x16x32_bf16 v[52:55], v[216:219], v[148:151], v[52:55]
	v_mfma_f32_16x16x32_bf16 v[44:47], v[224:227], v[148:151], v[44:47]
	v_mfma_f32_16x16x32_bf16 v[36:39], v[216:219], v[156:159], v[36:39]
	v_mfma_f32_16x16x32_bf16 v[28:31], v[224:227], v[156:159], v[28:31]
	v_mfma_f32_16x16x32_bf16 v[20:23], v[216:219], v[196:199], v[20:23]
	v_mfma_f32_16x16x32_bf16 v[12:15], v[224:227], v[196:199], v[12:15]
	v_mfma_f32_16x16x32_bf16 v[8:11], v[216:219], v[208:211], v[8:11]
	v_mfma_f32_16x16x32_bf16 v[4:7], v[224:227], v[208:211], v[4:7]
	v_mfma_f32_16x16x32_bf16 v[52:55], v[220:223], v[152:155], v[52:55]
	v_mfma_f32_16x16x32_bf16 v[44:47], v[228:231], v[152:155], v[44:47]
	v_mfma_f32_16x16x32_bf16 v[36:39], v[220:223], v[160:163], v[36:39]
	v_mfma_f32_16x16x32_bf16 v[28:31], v[228:231], v[160:163], v[28:31]
	v_mfma_f32_16x16x32_bf16 v[20:23], v[220:223], v[200:203], v[20:23]
	v_mfma_f32_16x16x32_bf16 v[12:15], v[228:231], v[200:203], v[12:15]
	s_setprio 2
	s_barrier
	v_mfma_f32_16x16x32_bf16 v[8:11], v[220:223], v[212:215], v[8:11]
	v_mfma_f32_16x16x32_bf16 v[4:7], v[228:231], v[212:215], v[4:7]
	s_setprio 0
	s_add_u32 s42, s42, 0x100
	s_addc_u32 s43, s43, 0
	s_add_u32 s58, s58, 0x100
	s_addc_u32 s59, s59, 0
	s_cmp_ge_u32 s78, s68
	s_mov_b32 s44, s78
	s_cbranch_scc0 .LBB0_514
